# GEMM epilogue tile stores write-through (sc1) on top of PRE spread + fin12 + g1 gain batch
# baseline (speedup 1.0000x reference)
.LBB0_157:
	s_lshl_b32 s38, s79, 10
	s_and_b32 s38, s38, 0x400
	v_add_u32_e32 v161, s38, v158
	ds_read_b32 v162, v161
	v_lshl_add_u32 v154, s78, 8, v156
	s_lshl_b32 s38, s77, 8
	v_ashrrev_i32_e32 v155, 31, v154
	s_ashr_i32 s39, s38, 31
	v_lshlrev_b64 v[164:165], 13, v[154:155]
	v_lshl_add_u64 v[164:165], s[30:31], 0, v[164:165]
	s_lshl_b64 s[38:39], s[38:39], 1
	v_lshl_add_u64 v[164:165], v[164:165], 0, s[38:39]
	s_waitcnt lgkmcnt(0)
	v_pk_mul_f32 v[136:137], v[136:137], v[162:163] op_sel_hi:[1,0]
	v_pk_mul_f32 v[134:135], v[134:135], v[162:163] op_sel_hi:[1,0]
	v_pk_mul_f32 v[132:133], v[132:133], v[162:163] op_sel_hi:[1,0]
	v_pk_mul_f32 v[130:131], v[130:131], v[162:163] op_sel_hi:[1,0]
	v_lshl_add_u64 v[164:165], v[164:165], 0, s[50:51]
	v_max_f32_e32 v137, 0, v137
	v_max_f32_e32 v136, 0, v136
	v_max_f32_e32 v135, 0, v135
	v_max_f32_e32 v134, 0, v134
	v_max_f32_e32 v133, 0, v133
	v_max_f32_e32 v132, 0, v132
	v_max_f32_e32 v131, 0, v131
	v_max_f32_e32 v130, 0, v130
	v_pk_mul_f32 v[124:125], v[124:125], v[162:163] op_sel_hi:[1,0]
	v_pk_mul_f32 v[122:123], v[122:123], v[162:163] op_sel_hi:[1,0]
	v_lshl_add_u64 v[164:165], v[164:165], 0, v[152:153]
	v_pk_mul_f32 v[136:137], v[136:137], v[136:137]
	v_pk_mul_f32 v[134:135], v[134:135], v[134:135]
	v_pk_mul_f32 v[166:167], v[132:133], v[132:133]
	v_pk_mul_f32 v[132:133], v[130:131], v[130:131]
	v_cvt_pk_bf16_f32 v130, v134, v135
	v_cvt_pk_bf16_f32 v131, v136, v137
	v_pk_mul_f32 v[128:129], v[128:129], v[162:163] op_sel_hi:[1,0]
	v_pk_mul_f32 v[126:127], v[126:127], v[162:163] op_sel_hi:[1,0]
	v_max_f32_e32 v125, 0, v125
	v_max_f32_e32 v124, 0, v124
	v_max_f32_e32 v123, 0, v123
	v_max_f32_e32 v122, 0, v122
	v_cvt_pk_bf16_f32 v132, v132, v133
	v_cvt_pk_bf16_f32 v133, v166, v167
	global_store_dwordx4 v[164:165], v[130:133], off sc1
	v_max_f32_e32 v129, 0, v129
	v_max_f32_e32 v128, 0, v128
	v_max_f32_e32 v127, 0, v127
	v_max_f32_e32 v126, 0, v126
	v_pk_mul_f32 v[130:131], v[124:125], v[124:125]
	v_pk_mul_f32 v[124:125], v[122:123], v[122:123]
	v_pk_mul_f32 v[128:129], v[128:129], v[128:129]
	v_pk_mul_f32 v[126:127], v[126:127], v[126:127]
	s_and_b64 vcc, exec, s[40:41]
	v_cvt_pk_bf16_f32 v122, v126, v127
	v_cvt_pk_bf16_f32 v123, v128, v129
	v_cvt_pk_bf16_f32 v124, v124, v125
	v_cvt_pk_bf16_f32 v125, v130, v131
	global_store_dwordx4 v[164:165], v[122:125], off offset:256 sc1
	ds_read_b32 v124, v161 offset:64
	s_waitcnt lgkmcnt(0)
	v_pk_mul_f32 v[120:121], v[120:121], v[124:125] op_sel_hi:[1,0]
	v_or_b32_e32 v122, 16, v154
	v_ashrrev_i32_e32 v123, 31, v122
	v_lshlrev_b64 v[122:123], 13, v[122:123]
	v_lshl_add_u64 v[122:123], s[30:31], 0, v[122:123]
	v_lshl_add_u64 v[122:123], v[122:123], 0, s[38:39]
	v_pk_mul_f32 v[118:119], v[118:119], v[124:125] op_sel_hi:[1,0]
	v_pk_mul_f32 v[116:117], v[116:117], v[124:125] op_sel_hi:[1,0]
	v_pk_mul_f32 v[114:115], v[114:115], v[124:125] op_sel_hi:[1,0]
	v_lshl_add_u64 v[122:123], v[122:123], 0, s[50:51]
	v_max_f32_e32 v121, 0, v121
	v_max_f32_e32 v120, 0, v120
	v_max_f32_e32 v119, 0, v119
	v_max_f32_e32 v118, 0, v118
	v_max_f32_e32 v117, 0, v117
	v_max_f32_e32 v116, 0, v116
	v_max_f32_e32 v115, 0, v115
	v_max_f32_e32 v114, 0, v114
	v_pk_mul_f32 v[108:109], v[108:109], v[124:125] op_sel_hi:[1,0]
	v_pk_mul_f32 v[106:107], v[106:107], v[124:125] op_sel_hi:[1,0]
	v_lshl_add_u64 v[122:123], v[122:123], 0, v[152:153]
	v_pk_mul_f32 v[120:121], v[120:121], v[120:121]
	v_pk_mul_f32 v[118:119], v[118:119], v[118:119]
	v_pk_mul_f32 v[126:127], v[116:117], v[116:117]
	v_pk_mul_f32 v[116:117], v[114:115], v[114:115]
	v_cvt_pk_bf16_f32 v114, v118, v119
	v_cvt_pk_bf16_f32 v115, v120, v121
	v_pk_mul_f32 v[112:113], v[112:113], v[124:125] op_sel_hi:[1,0]
	v_pk_mul_f32 v[110:111], v[110:111], v[124:125] op_sel_hi:[1,0]
	v_max_f32_e32 v109, 0, v109
	v_max_f32_e32 v108, 0, v108
	v_max_f32_e32 v107, 0, v107
	v_max_f32_e32 v106, 0, v106
	v_cvt_pk_bf16_f32 v116, v116, v117
	v_cvt_pk_bf16_f32 v117, v126, v127
	global_store_dwordx4 v[122:123], v[114:117], off sc1
	v_max_f32_e32 v113, 0, v113
	v_max_f32_e32 v112, 0, v112
	v_max_f32_e32 v111, 0, v111
	v_max_f32_e32 v110, 0, v110
	v_pk_mul_f32 v[114:115], v[108:109], v[108:109]
	v_pk_mul_f32 v[108:109], v[106:107], v[106:107]
	v_pk_mul_f32 v[112:113], v[112:113], v[112:113]
	v_pk_mul_f32 v[110:111], v[110:111], v[110:111]
	s_nop 0
	v_cvt_pk_bf16_f32 v106, v110, v111
	v_cvt_pk_bf16_f32 v107, v112, v113
	v_cvt_pk_bf16_f32 v108, v108, v109
	v_cvt_pk_bf16_f32 v109, v114, v115
	global_store_dwordx4 v[122:123], v[106:109], off offset:256 sc1
	ds_read_b32 v108, v161 offset:128
	s_waitcnt lgkmcnt(0)
	v_pk_mul_f32 v[104:105], v[104:105], v[108:109] op_sel_hi:[1,0]
	v_or_b32_e32 v106, 32, v154
	v_ashrrev_i32_e32 v107, 31, v106
	v_lshlrev_b64 v[106:107], 13, v[106:107]
	v_lshl_add_u64 v[106:107], s[30:31], 0, v[106:107]
	v_lshl_add_u64 v[106:107], v[106:107], 0, s[38:39]
	v_pk_mul_f32 v[102:103], v[102:103], v[108:109] op_sel_hi:[1,0]
	v_pk_mul_f32 v[100:101], v[100:101], v[108:109] op_sel_hi:[1,0]
	v_pk_mul_f32 v[98:99], v[98:99], v[108:109] op_sel_hi:[1,0]
	v_lshl_add_u64 v[106:107], v[106:107], 0, s[50:51]
	v_max_f32_e32 v105, 0, v105
	v_max_f32_e32 v104, 0, v104
	v_max_f32_e32 v103, 0, v103
	v_max_f32_e32 v102, 0, v102
	v_max_f32_e32 v101, 0, v101
	v_max_f32_e32 v100, 0, v100
	v_max_f32_e32 v99, 0, v99
	v_max_f32_e32 v98, 0, v98
	v_pk_mul_f32 v[92:93], v[92:93], v[108:109] op_sel_hi:[1,0]
	v_pk_mul_f32 v[90:91], v[90:91], v[108:109] op_sel_hi:[1,0]
	v_lshl_add_u64 v[106:107], v[106:107], 0, v[152:153]
	v_pk_mul_f32 v[104:105], v[104:105], v[104:105]
	v_pk_mul_f32 v[102:103], v[102:103], v[102:103]
	v_pk_mul_f32 v[110:111], v[100:101], v[100:101]
	v_pk_mul_f32 v[100:101], v[98:99], v[98:99]
	v_cvt_pk_bf16_f32 v98, v102, v103
	v_cvt_pk_bf16_f32 v99, v104, v105
	v_pk_mul_f32 v[96:97], v[96:97], v[108:109] op_sel_hi:[1,0]
	v_pk_mul_f32 v[94:95], v[94:95], v[108:109] op_sel_hi:[1,0]
	v_max_f32_e32 v93, 0, v93
	v_max_f32_e32 v92, 0, v92
	v_max_f32_e32 v91, 0, v91
	v_max_f32_e32 v90, 0, v90
	v_cvt_pk_bf16_f32 v100, v100, v101
	v_cvt_pk_bf16_f32 v101, v110, v111
	global_store_dwordx4 v[106:107], v[98:101], off sc1
	v_max_f32_e32 v97, 0, v97
	v_max_f32_e32 v96, 0, v96
	v_max_f32_e32 v95, 0, v95
	v_max_f32_e32 v94, 0, v94
	v_pk_mul_f32 v[98:99], v[92:93], v[92:93]
	v_pk_mul_f32 v[92:93], v[90:91], v[90:91]
	v_pk_mul_f32 v[96:97], v[96:97], v[96:97]
	v_pk_mul_f32 v[94:95], v[94:95], v[94:95]
	s_nop 0
	v_cvt_pk_bf16_f32 v90, v94, v95
	v_cvt_pk_bf16_f32 v91, v96, v97
	v_cvt_pk_bf16_f32 v92, v92, v93
	v_cvt_pk_bf16_f32 v93, v98, v99
	global_store_dwordx4 v[106:107], v[90:93], off offset:256 sc1
	ds_read_b32 v92, v161 offset:192
	s_waitcnt lgkmcnt(0)
	v_pk_mul_f32 v[88:89], v[88:89], v[92:93] op_sel_hi:[1,0]
	v_or_b32_e32 v90, 48, v154
	v_ashrrev_i32_e32 v91, 31, v90
	v_lshlrev_b64 v[90:91], 13, v[90:91]
	v_lshl_add_u64 v[90:91], s[30:31], 0, v[90:91]
	v_lshl_add_u64 v[90:91], v[90:91], 0, s[38:39]
	v_pk_mul_f32 v[86:87], v[86:87], v[92:93] op_sel_hi:[1,0]
	v_pk_mul_f32 v[84:85], v[84:85], v[92:93] op_sel_hi:[1,0]
	v_pk_mul_f32 v[82:83], v[82:83], v[92:93] op_sel_hi:[1,0]
	v_lshl_add_u64 v[90:91], v[90:91], 0, s[50:51]
	v_max_f32_e32 v89, 0, v89
	v_max_f32_e32 v88, 0, v88
	v_max_f32_e32 v87, 0, v87
	v_max_f32_e32 v86, 0, v86
	v_max_f32_e32 v85, 0, v85
	v_max_f32_e32 v84, 0, v84
	v_max_f32_e32 v83, 0, v83
	v_max_f32_e32 v82, 0, v82
	v_pk_mul_f32 v[76:77], v[76:77], v[92:93] op_sel_hi:[1,0]
	v_pk_mul_f32 v[74:75], v[74:75], v[92:93] op_sel_hi:[1,0]
	v_lshl_add_u64 v[90:91], v[90:91], 0, v[152:153]
	v_pk_mul_f32 v[88:89], v[88:89], v[88:89]
	v_pk_mul_f32 v[86:87], v[86:87], v[86:87]
	v_pk_mul_f32 v[94:95], v[84:85], v[84:85]
	v_pk_mul_f32 v[84:85], v[82:83], v[82:83]
	v_cvt_pk_bf16_f32 v82, v86, v87
	v_cvt_pk_bf16_f32 v83, v88, v89
	v_pk_mul_f32 v[80:81], v[80:81], v[92:93] op_sel_hi:[1,0]
	v_pk_mul_f32 v[78:79], v[78:79], v[92:93] op_sel_hi:[1,0]
	v_max_f32_e32 v77, 0, v77
	v_max_f32_e32 v76, 0, v76
	v_max_f32_e32 v75, 0, v75
	v_max_f32_e32 v74, 0, v74
	v_cvt_pk_bf16_f32 v84, v84, v85
	v_cvt_pk_bf16_f32 v85, v94, v95
	global_store_dwordx4 v[90:91], v[82:85], off sc1
	v_max_f32_e32 v81, 0, v81
	v_max_f32_e32 v80, 0, v80
	v_max_f32_e32 v79, 0, v79
	v_max_f32_e32 v78, 0, v78
	v_pk_mul_f32 v[82:83], v[76:77], v[76:77]
	v_pk_mul_f32 v[76:77], v[74:75], v[74:75]
	v_pk_mul_f32 v[80:81], v[80:81], v[80:81]
	v_pk_mul_f32 v[78:79], v[78:79], v[78:79]
	s_nop 0
	v_cvt_pk_bf16_f32 v74, v78, v79
	v_cvt_pk_bf16_f32 v75, v80, v81
	v_cvt_pk_bf16_f32 v76, v76, v77
	v_cvt_pk_bf16_f32 v77, v82, v83
	global_store_dwordx4 v[90:91], v[74:77], off offset:256 sc1
	ds_read_b32 v76, v161 offset:512
	s_waitcnt lgkmcnt(0)
	v_pk_mul_f32 v[72:73], v[72:73], v[76:77] op_sel_hi:[1,0]
	v_add_u32_e32 v74, 0x80, v154
	v_ashrrev_i32_e32 v75, 31, v74
	v_lshlrev_b64 v[74:75], 13, v[74:75]
	v_lshl_add_u64 v[74:75], s[30:31], 0, v[74:75]
	v_lshl_add_u64 v[74:75], v[74:75], 0, s[38:39]
	v_pk_mul_f32 v[70:71], v[70:71], v[76:77] op_sel_hi:[1,0]
	v_pk_mul_f32 v[68:69], v[68:69], v[76:77] op_sel_hi:[1,0]
	v_pk_mul_f32 v[66:67], v[66:67], v[76:77] op_sel_hi:[1,0]
	v_lshl_add_u64 v[74:75], v[74:75], 0, s[50:51]
	v_max_f32_e32 v73, 0, v73
	v_max_f32_e32 v72, 0, v72
	v_max_f32_e32 v71, 0, v71
	v_max_f32_e32 v70, 0, v70
	v_max_f32_e32 v69, 0, v69
	v_max_f32_e32 v68, 0, v68
	v_max_f32_e32 v67, 0, v67
	v_max_f32_e32 v66, 0, v66
	v_pk_mul_f32 v[60:61], v[60:61], v[76:77] op_sel_hi:[1,0]
	v_pk_mul_f32 v[58:59], v[58:59], v[76:77] op_sel_hi:[1,0]
	v_lshl_add_u64 v[74:75], v[74:75], 0, v[152:153]
	v_pk_mul_f32 v[72:73], v[72:73], v[72:73]
	v_pk_mul_f32 v[70:71], v[70:71], v[70:71]
	v_pk_mul_f32 v[78:79], v[68:69], v[68:69]
	v_pk_mul_f32 v[68:69], v[66:67], v[66:67]
	v_cvt_pk_bf16_f32 v66, v70, v71
	v_cvt_pk_bf16_f32 v67, v72, v73
	v_pk_mul_f32 v[64:65], v[64:65], v[76:77] op_sel_hi:[1,0]
	v_pk_mul_f32 v[62:63], v[62:63], v[76:77] op_sel_hi:[1,0]
	v_max_f32_e32 v61, 0, v61
	v_max_f32_e32 v60, 0, v60
	v_max_f32_e32 v59, 0, v59
	v_max_f32_e32 v58, 0, v58
	v_cvt_pk_bf16_f32 v68, v68, v69
	v_cvt_pk_bf16_f32 v69, v78, v79
	global_store_dwordx4 v[74:75], v[66:69], off sc1
	v_max_f32_e32 v65, 0, v65
	v_max_f32_e32 v64, 0, v64
	v_max_f32_e32 v63, 0, v63
	v_max_f32_e32 v62, 0, v62
	v_pk_mul_f32 v[66:67], v[60:61], v[60:61]
	v_pk_mul_f32 v[60:61], v[58:59], v[58:59]
	v_pk_mul_f32 v[64:65], v[64:65], v[64:65]
	v_pk_mul_f32 v[62:63], v[62:63], v[62:63]
	s_nop 0
	v_cvt_pk_bf16_f32 v58, v62, v63
	v_cvt_pk_bf16_f32 v59, v64, v65
	v_cvt_pk_bf16_f32 v60, v60, v61
	v_cvt_pk_bf16_f32 v61, v66, v67
	global_store_dwordx4 v[74:75], v[58:61], off offset:256 sc1
	ds_read_b32 v60, v161 offset:576
	s_waitcnt lgkmcnt(0)
	v_pk_mul_f32 v[56:57], v[56:57], v[60:61] op_sel_hi:[1,0]
	v_add_u32_e32 v58, 0x90, v154
	v_ashrrev_i32_e32 v59, 31, v58
	v_lshlrev_b64 v[58:59], 13, v[58:59]
	v_lshl_add_u64 v[58:59], s[30:31], 0, v[58:59]
	v_lshl_add_u64 v[58:59], v[58:59], 0, s[38:39]
	v_pk_mul_f32 v[54:55], v[54:55], v[60:61] op_sel_hi:[1,0]
	v_pk_mul_f32 v[52:53], v[52:53], v[60:61] op_sel_hi:[1,0]
	v_pk_mul_f32 v[50:51], v[50:51], v[60:61] op_sel_hi:[1,0]
	v_lshl_add_u64 v[58:59], v[58:59], 0, s[50:51]
	v_max_f32_e32 v57, 0, v57
	v_max_f32_e32 v56, 0, v56
	v_max_f32_e32 v55, 0, v55
	v_max_f32_e32 v54, 0, v54
	v_max_f32_e32 v53, 0, v53
	v_max_f32_e32 v52, 0, v52
	v_max_f32_e32 v51, 0, v51
	v_max_f32_e32 v50, 0, v50
	v_pk_mul_f32 v[44:45], v[44:45], v[60:61] op_sel_hi:[1,0]
	v_pk_mul_f32 v[42:43], v[42:43], v[60:61] op_sel_hi:[1,0]
	v_lshl_add_u64 v[58:59], v[58:59], 0, v[152:153]
	v_pk_mul_f32 v[56:57], v[56:57], v[56:57]
	v_pk_mul_f32 v[54:55], v[54:55], v[54:55]
	v_pk_mul_f32 v[62:63], v[52:53], v[52:53]
	v_pk_mul_f32 v[52:53], v[50:51], v[50:51]
	v_cvt_pk_bf16_f32 v50, v54, v55
	v_cvt_pk_bf16_f32 v51, v56, v57
	v_pk_mul_f32 v[48:49], v[48:49], v[60:61] op_sel_hi:[1,0]
	v_pk_mul_f32 v[46:47], v[46:47], v[60:61] op_sel_hi:[1,0]
	v_max_f32_e32 v45, 0, v45
	v_max_f32_e32 v44, 0, v44
	v_max_f32_e32 v43, 0, v43
	v_max_f32_e32 v42, 0, v42
	v_cvt_pk_bf16_f32 v52, v52, v53
	v_cvt_pk_bf16_f32 v53, v62, v63
	global_store_dwordx4 v[58:59], v[50:53], off sc1
	v_max_f32_e32 v49, 0, v49
	v_max_f32_e32 v48, 0, v48
	v_max_f32_e32 v47, 0, v47
	v_max_f32_e32 v46, 0, v46
	v_pk_mul_f32 v[50:51], v[44:45], v[44:45]
	v_pk_mul_f32 v[44:45], v[42:43], v[42:43]
	v_pk_mul_f32 v[48:49], v[48:49], v[48:49]
	v_pk_mul_f32 v[46:47], v[46:47], v[46:47]
	s_nop 0
	v_cvt_pk_bf16_f32 v42, v46, v47
	v_cvt_pk_bf16_f32 v43, v48, v49
	v_cvt_pk_bf16_f32 v44, v44, v45
	v_cvt_pk_bf16_f32 v45, v50, v51
	global_store_dwordx4 v[58:59], v[42:45], off offset:256 sc1
	ds_read_b32 v44, v161 offset:640
	s_waitcnt lgkmcnt(0)
	v_pk_mul_f32 v[40:41], v[40:41], v[44:45] op_sel_hi:[1,0]
	v_add_u32_e32 v42, 0xa0, v154
	v_ashrrev_i32_e32 v43, 31, v42
	v_lshlrev_b64 v[42:43], 13, v[42:43]
	v_lshl_add_u64 v[42:43], s[30:31], 0, v[42:43]
	v_lshl_add_u64 v[42:43], v[42:43], 0, s[38:39]
	v_pk_mul_f32 v[38:39], v[38:39], v[44:45] op_sel_hi:[1,0]
	v_pk_mul_f32 v[36:37], v[36:37], v[44:45] op_sel_hi:[1,0]
	v_pk_mul_f32 v[34:35], v[34:35], v[44:45] op_sel_hi:[1,0]
	v_lshl_add_u64 v[42:43], v[42:43], 0, s[50:51]
	v_max_f32_e32 v41, 0, v41
	v_max_f32_e32 v40, 0, v40
	v_max_f32_e32 v39, 0, v39
	v_max_f32_e32 v38, 0, v38
	v_max_f32_e32 v37, 0, v37
	v_max_f32_e32 v36, 0, v36
	v_max_f32_e32 v35, 0, v35
	v_max_f32_e32 v34, 0, v34
	v_pk_mul_f32 v[28:29], v[28:29], v[44:45] op_sel_hi:[1,0]
	v_pk_mul_f32 v[26:27], v[26:27], v[44:45] op_sel_hi:[1,0]
	v_lshl_add_u64 v[42:43], v[42:43], 0, v[152:153]
	v_pk_mul_f32 v[40:41], v[40:41], v[40:41]
	v_pk_mul_f32 v[38:39], v[38:39], v[38:39]
	v_pk_mul_f32 v[46:47], v[36:37], v[36:37]
	v_pk_mul_f32 v[36:37], v[34:35], v[34:35]
	v_cvt_pk_bf16_f32 v34, v38, v39
	v_cvt_pk_bf16_f32 v35, v40, v41
	v_pk_mul_f32 v[32:33], v[32:33], v[44:45] op_sel_hi:[1,0]
	v_pk_mul_f32 v[30:31], v[30:31], v[44:45] op_sel_hi:[1,0]
	v_max_f32_e32 v29, 0, v29
	v_max_f32_e32 v28, 0, v28
	v_max_f32_e32 v27, 0, v27
	v_max_f32_e32 v26, 0, v26
	v_cvt_pk_bf16_f32 v36, v36, v37
	v_cvt_pk_bf16_f32 v37, v46, v47
	global_store_dwordx4 v[42:43], v[34:37], off sc1
	v_max_f32_e32 v33, 0, v33
	v_max_f32_e32 v32, 0, v32
	v_max_f32_e32 v31, 0, v31
	v_max_f32_e32 v30, 0, v30
	v_pk_mul_f32 v[34:35], v[28:29], v[28:29]
	v_pk_mul_f32 v[28:29], v[26:27], v[26:27]
	v_pk_mul_f32 v[32:33], v[32:33], v[32:33]
	v_pk_mul_f32 v[30:31], v[30:31], v[30:31]
	s_nop 0
	v_cvt_pk_bf16_f32 v26, v30, v31
	v_cvt_pk_bf16_f32 v27, v32, v33
	v_cvt_pk_bf16_f32 v28, v28, v29
	v_cvt_pk_bf16_f32 v29, v34, v35
	global_store_dwordx4 v[42:43], v[26:29], off offset:256 sc1
	ds_read_b32 v28, v161 offset:704
	s_waitcnt lgkmcnt(0)
	v_pk_mul_f32 v[24:25], v[24:25], v[28:29] op_sel_hi:[1,0]
	v_add_u32_e32 v26, 0xb0, v154
	v_ashrrev_i32_e32 v27, 31, v26
	v_lshlrev_b64 v[26:27], 13, v[26:27]
	v_lshl_add_u64 v[26:27], s[30:31], 0, v[26:27]
	v_lshl_add_u64 v[26:27], v[26:27], 0, s[38:39]
	v_pk_mul_f32 v[22:23], v[22:23], v[28:29] op_sel_hi:[1,0]
	v_pk_mul_f32 v[20:21], v[20:21], v[28:29] op_sel_hi:[1,0]
	v_pk_mul_f32 v[18:19], v[18:19], v[28:29] op_sel_hi:[1,0]
	v_lshl_add_u64 v[26:27], v[26:27], 0, s[50:51]
	v_max_f32_e32 v25, 0, v25
	v_max_f32_e32 v24, 0, v24
	v_max_f32_e32 v23, 0, v23
	v_max_f32_e32 v22, 0, v22
	v_max_f32_e32 v21, 0, v21
	v_max_f32_e32 v20, 0, v20
	v_max_f32_e32 v19, 0, v19
	v_max_f32_e32 v18, 0, v18
	v_pk_mul_f32 v[12:13], v[12:13], v[28:29] op_sel_hi:[1,0]
	v_pk_mul_f32 v[10:11], v[10:11], v[28:29] op_sel_hi:[1,0]
	v_lshl_add_u64 v[26:27], v[26:27], 0, v[152:153]
	v_pk_mul_f32 v[24:25], v[24:25], v[24:25]
	v_pk_mul_f32 v[22:23], v[22:23], v[22:23]
	v_pk_mul_f32 v[30:31], v[20:21], v[20:21]
	v_pk_mul_f32 v[20:21], v[18:19], v[18:19]
	v_cvt_pk_bf16_f32 v18, v22, v23
	v_cvt_pk_bf16_f32 v19, v24, v25
	v_pk_mul_f32 v[16:17], v[16:17], v[28:29] op_sel_hi:[1,0]
	v_pk_mul_f32 v[14:15], v[14:15], v[28:29] op_sel_hi:[1,0]
	v_max_f32_e32 v13, 0, v13
	v_max_f32_e32 v12, 0, v12
	v_max_f32_e32 v11, 0, v11
	v_max_f32_e32 v10, 0, v10
	v_cvt_pk_bf16_f32 v20, v20, v21
	v_cvt_pk_bf16_f32 v21, v30, v31
	global_store_dwordx4 v[26:27], v[18:21], off sc1
	v_max_f32_e32 v17, 0, v17
	v_max_f32_e32 v16, 0, v16
	v_max_f32_e32 v15, 0, v15
	v_max_f32_e32 v14, 0, v14
	v_pk_mul_f32 v[18:19], v[12:13], v[12:13]
	v_pk_mul_f32 v[12:13], v[10:11], v[10:11]
	v_pk_mul_f32 v[16:17], v[16:17], v[16:17]
	v_pk_mul_f32 v[14:15], v[14:15], v[14:15]
	s_mov_b64 s[38:39], -1
	v_cvt_pk_bf16_f32 v10, v14, v15
	v_cvt_pk_bf16_f32 v11, v16, v17
	v_cvt_pk_bf16_f32 v12, v12, v13
	v_cvt_pk_bf16_f32 v13, v18, v19
	global_store_dwordx4 v[26:27], v[10:13], off offset:256 sc1
	s_cbranch_vccnz .LBB0_144
	s_waitcnt vmcnt(0)
	v_add_f32_e32 v10, v6, v7
	v_add_f32_e32 v11, v8, v9
	v_add_f32_e32 v10, v10, v11
	v_add_f32_e32 v11, v2, v3
	v_add_f32_e32 v12, v4, v5
	v_add_f32_e32 v11, v11, v12
	v_add_f32_e32 v10, v11, v10
	ds_bpermute_b32 v11, v1, v10
	s_and_saveexec_b64 s[38:39], s[36:37]
	s_cbranch_execz .LBB0_160
	s_waitcnt lgkmcnt(0)
	v_add_f32_e32 v10, v10, v11
	v_fmamk_f32 v10, v10, 0x3a800000, v220
	v_rsq_f32_e32 v10, v10
	s_lshl_b32 s40, s76, 10
	s_and_b32 s40, s40, 0x400
	v_add_u32_e32 v11, s40, v159
	ds_write_b32 v11, v10

.LBB0_363:
	s_add_i32 s84, s72, 2
	s_add_u32 s85, s40, 0x80
	s_addc_u32 s73, s41, 0
	s_add_i32 s87, 0, 0x10000
	s_cmp_eq_u32 s81, s72
	s_cselect_b32 s73, s56, s73
	s_cselect_b32 s72, s57, s85
	s_cselect_b32 s95, s59, s83
	s_cselect_b32 s94, s61, s82
	s_add_i32 s85, 0, 0x14000
	v_add_u32_e32 v142, s87, v196
	v_add_u32_e32 v170, s85, v196
	ds_read_b128 v[130:133], v142
	ds_read_b128 v[134:137], v142 offset:1024
	ds_read_b128 v[138:141], v142 offset:2048
	ds_read_b128 v[142:145], v142 offset:3072
	ds_read_b128 v[146:149], v170
	ds_read_b128 v[150:153], v170 offset:1024
	ds_read_b128 v[154:157], v170 offset:2048
	ds_read_b128 v[170:173], v170 offset:3072
	v_lshl_add_u64 v[214:215], s[40:41], 0, v[166:167]
	s_add_i32 m0, s46, 0xc000
	ds_read_b128 v[174:177], v200
	ds_read_b128 v[178:181], v200 offset:1024
	ds_read_b128 v[182:185], v200 offset:2048
	ds_read_b128 v[186:189], v200 offset:3072
	ds_read_b128 v[190:193], v200 offset:4096
	ds_read_b128 v[202:205], v200 offset:5120
	ds_read_b128 v[206:209], v200 offset:6144
	ds_read_b128 v[210:213], v200 offset:7168
	global_load_lds_dwordx4 v[214:215], off
	v_lshl_add_u64 v[214:215], s[40:41], 0, v[168:169]
	s_add_i32 m0, s46, 0xe000
	s_nop 0
	global_load_lds_dwordx4 v[214:215], off
	s_waitcnt vmcnt(8)
	s_waitcnt lgkmcnt(0)
	s_barrier
	s_setprio 1
	s_waitcnt lgkmcnt(0)
	v_mfma_f32_16x16x32_bf16 v[126:129], v[130:133], v[174:177], v[126:129]
	v_mfma_f32_16x16x32_bf16 v[122:125], v[138:141], v[174:177], v[122:125]
	v_mfma_f32_16x16x32_bf16 v[110:113], v[130:133], v[182:185], v[110:113]
	v_mfma_f32_16x16x32_bf16 v[106:109], v[138:141], v[182:185], v[106:109]
	v_mfma_f32_16x16x32_bf16 v[94:97], v[130:133], v[190:193], v[94:97]
	v_mfma_f32_16x16x32_bf16 v[90:93], v[138:141], v[190:193], v[90:93]
	v_mfma_f32_16x16x32_bf16 v[78:81], v[130:133], v[206:209], v[78:81]
	v_mfma_f32_16x16x32_bf16 v[74:77], v[138:141], v[206:209], v[74:77]
	v_mfma_f32_16x16x32_bf16 v[126:129], v[134:137], v[178:181], v[126:129]
	v_mfma_f32_16x16x32_bf16 v[122:125], v[142:145], v[178:181], v[122:125]
	v_mfma_f32_16x16x32_bf16 v[110:113], v[134:137], v[186:189], v[110:113]
	v_mfma_f32_16x16x32_bf16 v[106:109], v[142:145], v[186:189], v[106:109]
	v_mfma_f32_16x16x32_bf16 v[94:97], v[134:137], v[202:205], v[94:97]
	v_mfma_f32_16x16x32_bf16 v[90:93], v[142:145], v[202:205], v[90:93]
	v_mfma_f32_16x16x32_bf16 v[78:81], v[134:137], v[210:213], v[78:81]
	v_mfma_f32_16x16x32_bf16 v[74:77], v[142:145], v[210:213], v[74:77]
	s_setprio 0
	s_setprio 1
	v_mfma_f32_16x16x32_bf16 v[118:121], v[146:149], v[174:177], v[118:121]
	v_mfma_f32_16x16x32_bf16 v[114:117], v[154:157], v[174:177], v[114:117]
	v_mfma_f32_16x16x32_bf16 v[102:105], v[146:149], v[182:185], v[102:105]
	v_mfma_f32_16x16x32_bf16 v[98:101], v[154:157], v[182:185], v[98:101]
	v_mfma_f32_16x16x32_bf16 v[86:89], v[146:149], v[190:193], v[86:89]
	v_mfma_f32_16x16x32_bf16 v[82:85], v[154:157], v[190:193], v[82:85]
	v_mfma_f32_16x16x32_bf16 v[70:73], v[146:149], v[206:209], v[70:73]
	v_mfma_f32_16x16x32_bf16 v[66:69], v[154:157], v[206:209], v[66:69]
	v_mfma_f32_16x16x32_bf16 v[118:121], v[150:153], v[178:181], v[118:121]
	v_mfma_f32_16x16x32_bf16 v[114:117], v[170:173], v[178:181], v[114:117]
	v_mfma_f32_16x16x32_bf16 v[102:105], v[150:153], v[186:189], v[102:105]
	v_mfma_f32_16x16x32_bf16 v[98:101], v[170:173], v[186:189], v[98:101]
	v_mfma_f32_16x16x32_bf16 v[86:89], v[150:153], v[202:205], v[86:89]
	v_mfma_f32_16x16x32_bf16 v[82:85], v[170:173], v[202:205], v[82:85]
	v_mfma_f32_16x16x32_bf16 v[70:73], v[150:153], v[210:213], v[70:73]
	v_mfma_f32_16x16x32_bf16 v[66:69], v[170:173], v[210:213], v[66:69]
	s_setprio 0
	s_barrier
	s_add_i32 s87, s87, s42
	v_lshl_add_u64 v[214:215], s[94:95], 0, v[162:163]
	s_mov_b32 m0, s87
	ds_read_b128 v[174:177], v200 offset:16384
	ds_read_b128 v[178:181], v200 offset:17408
	ds_read_b128 v[182:185], v200 offset:18432
	ds_read_b128 v[186:189], v200 offset:19456
	ds_read_b128 v[190:193], v200 offset:20480
	ds_read_b128 v[202:205], v200 offset:21504
	ds_read_b128 v[206:209], v200 offset:22528
	ds_read_b128 v[210:213], v200 offset:23552
	global_load_lds_dwordx4 v[214:215], off
	s_add_i32 m0, s87, 0x2000
	v_lshl_add_u64 v[216:217], s[94:95], 0, v[158:159]
	s_add_u32 s94, s94, s26
	s_addc_u32 s95, s95, 0
	s_add_i32 s85, s85, s42
	global_load_lds_dwordx4 v[216:217], off
	v_lshl_add_u64 v[218:219], s[94:95], 0, v[162:163]
	s_mov_b32 m0, s85
	v_lshl_add_u64 v[228:229], s[94:95], 0, v[158:159]
	global_load_lds_dwordx4 v[218:219], off
	s_add_i32 m0, s85, 0x2000
	v_lshl_add_u64 v[230:231], s[72:73], 0, v[164:165]
	global_load_lds_dwordx4 v[228:229], off
	s_mov_b32 m0, s46
	v_lshl_add_u64 v[232:233], s[72:73], 0, v[160:161]
	global_load_lds_dwordx4 v[230:231], off
	s_mov_b32 m0, s47
	s_nop 0
	global_load_lds_dwordx4 v[232:233], off
	s_waitcnt vmcnt(8)
	s_waitcnt lgkmcnt(0)
	s_barrier
	s_setprio 1
	s_waitcnt lgkmcnt(0)
	v_mfma_f32_16x16x32_bf16 v[62:65], v[130:133], v[174:177], v[62:65]
	v_mfma_f32_16x16x32_bf16 v[58:61], v[138:141], v[174:177], v[58:61]
	v_mfma_f32_16x16x32_bf16 v[46:49], v[130:133], v[182:185], v[46:49]
	v_mfma_f32_16x16x32_bf16 v[42:45], v[138:141], v[182:185], v[42:45]
	v_mfma_f32_16x16x32_bf16 v[30:33], v[130:133], v[190:193], v[30:33]
	v_mfma_f32_16x16x32_bf16 v[26:29], v[138:141], v[190:193], v[26:29]
	v_mfma_f32_16x16x32_bf16 v[14:17], v[130:133], v[206:209], v[14:17]
	v_mfma_f32_16x16x32_bf16 v[10:13], v[138:141], v[206:209], v[10:13]
	v_mfma_f32_16x16x32_bf16 v[62:65], v[134:137], v[178:181], v[62:65]
	v_mfma_f32_16x16x32_bf16 v[58:61], v[142:145], v[178:181], v[58:61]
	v_mfma_f32_16x16x32_bf16 v[46:49], v[134:137], v[186:189], v[46:49]
	v_mfma_f32_16x16x32_bf16 v[42:45], v[142:145], v[186:189], v[42:45]
	v_mfma_f32_16x16x32_bf16 v[30:33], v[134:137], v[202:205], v[30:33]
	v_mfma_f32_16x16x32_bf16 v[26:29], v[142:145], v[202:205], v[26:29]
	v_mfma_f32_16x16x32_bf16 v[14:17], v[134:137], v[210:213], v[14:17]
	v_mfma_f32_16x16x32_bf16 v[10:13], v[142:145], v[210:213], v[10:13]
	s_setprio 0
	s_setprio 1
	v_mfma_f32_16x16x32_bf16 v[54:57], v[146:149], v[174:177], v[54:57]
	v_mfma_f32_16x16x32_bf16 v[50:53], v[154:157], v[174:177], v[50:53]
	v_mfma_f32_16x16x32_bf16 v[38:41], v[146:149], v[182:185], v[38:41]
	v_mfma_f32_16x16x32_bf16 v[34:37], v[154:157], v[182:185], v[34:37]
	v_mfma_f32_16x16x32_bf16 v[22:25], v[146:149], v[190:193], v[22:25]
	v_mfma_f32_16x16x32_bf16 v[18:21], v[154:157], v[190:193], v[18:21]
	v_mfma_f32_16x16x32_bf16 v[6:9], v[146:149], v[206:209], v[6:9]
	v_mfma_f32_16x16x32_bf16 v[2:5], v[154:157], v[206:209], v[2:5]
	v_mfma_f32_16x16x32_bf16 v[54:57], v[150:153], v[178:181], v[54:57]
	v_mfma_f32_16x16x32_bf16 v[50:53], v[170:173], v[178:181], v[50:53]
	v_mfma_f32_16x16x32_bf16 v[38:41], v[150:153], v[186:189], v[38:41]
	v_mfma_f32_16x16x32_bf16 v[34:37], v[170:173], v[186:189], v[34:37]
	v_mfma_f32_16x16x32_bf16 v[22:25], v[150:153], v[202:205], v[22:25]
	v_mfma_f32_16x16x32_bf16 v[18:21], v[170:173], v[202:205], v[18:21]
	v_mfma_f32_16x16x32_bf16 v[6:9], v[150:153], v[210:213], v[6:9]
	v_mfma_f32_16x16x32_bf16 v[2:5], v[170:173], v[210:213], v[2:5]
	s_setprio 0
	s_barrier
	s_add_i32 s85, 0, 0x18000
	s_add_i32 s87, 0, 0x1c000
	v_add_u32_e32 v142, s85, v196
	v_add_u32_e32 v170, s87, v196
	ds_read_b128 v[130:133], v142
	ds_read_b128 v[134:137], v142 offset:1024
	ds_read_b128 v[138:141], v142 offset:2048
	ds_read_b128 v[142:145], v142 offset:3072
	ds_read_b128 v[146:149], v170
	ds_read_b128 v[150:153], v170 offset:1024
	ds_read_b128 v[154:157], v170 offset:2048
	ds_read_b128 v[170:173], v170 offset:3072
	s_add_u32 s72, s72, s26
	s_addc_u32 s73, s73, 0
	s_mov_b32 m0, s68
	v_lshl_add_u64 v[234:235], s[72:73], 0, v[164:165]
	ds_read_b128 v[174:177], v200 offset:32768
	ds_read_b128 v[178:181], v200 offset:33792
	ds_read_b128 v[182:185], v200 offset:34816
	ds_read_b128 v[186:189], v200 offset:35840
	ds_read_b128 v[190:193], v200 offset:36864
	ds_read_b128 v[202:205], v200 offset:37888
	ds_read_b128 v[206:209], v200 offset:38912
	ds_read_b128 v[210:213], v200 offset:39936
	global_load_lds_dwordx4 v[234:235], off
	v_lshl_add_u64 v[234:235], s[72:73], 0, v[160:161]
	s_mov_b32 m0, s69
	s_nop 0
	global_load_lds_dwordx4 v[234:235], off
	s_waitcnt vmcnt(8)
	s_waitcnt lgkmcnt(0)
	s_barrier
	s_setprio 1
	s_waitcnt lgkmcnt(0)
	v_mfma_f32_16x16x32_bf16 v[126:129], v[130:133], v[174:177], v[126:129]
	v_mfma_f32_16x16x32_bf16 v[122:125], v[138:141], v[174:177], v[122:125]
	v_mfma_f32_16x16x32_bf16 v[110:113], v[130:133], v[182:185], v[110:113]
	v_mfma_f32_16x16x32_bf16 v[106:109], v[138:141], v[182:185], v[106:109]
	v_mfma_f32_16x16x32_bf16 v[94:97], v[130:133], v[190:193], v[94:97]
	v_mfma_f32_16x16x32_bf16 v[90:93], v[138:141], v[190:193], v[90:93]
	v_mfma_f32_16x16x32_bf16 v[78:81], v[130:133], v[206:209], v[78:81]
	v_mfma_f32_16x16x32_bf16 v[74:77], v[138:141], v[206:209], v[74:77]
	v_mfma_f32_16x16x32_bf16 v[126:129], v[134:137], v[178:181], v[126:129]
	v_mfma_f32_16x16x32_bf16 v[122:125], v[142:145], v[178:181], v[122:125]
	v_mfma_f32_16x16x32_bf16 v[110:113], v[134:137], v[186:189], v[110:113]
	v_mfma_f32_16x16x32_bf16 v[106:109], v[142:145], v[186:189], v[106:109]
	v_mfma_f32_16x16x32_bf16 v[94:97], v[134:137], v[202:205], v[94:97]
	v_mfma_f32_16x16x32_bf16 v[90:93], v[142:145], v[202:205], v[90:93]
	v_mfma_f32_16x16x32_bf16 v[78:81], v[134:137], v[210:213], v[78:81]
	v_mfma_f32_16x16x32_bf16 v[74:77], v[142:145], v[210:213], v[74:77]
	s_setprio 0
	s_setprio 1
	v_mfma_f32_16x16x32_bf16 v[118:121], v[146:149], v[174:177], v[118:121]
	v_mfma_f32_16x16x32_bf16 v[114:117], v[154:157], v[174:177], v[114:117]
	v_mfma_f32_16x16x32_bf16 v[102:105], v[146:149], v[182:185], v[102:105]
	v_mfma_f32_16x16x32_bf16 v[98:101], v[154:157], v[182:185], v[98:101]
	v_mfma_f32_16x16x32_bf16 v[86:89], v[146:149], v[190:193], v[86:89]
	v_mfma_f32_16x16x32_bf16 v[82:85], v[154:157], v[190:193], v[82:85]
	v_mfma_f32_16x16x32_bf16 v[70:73], v[146:149], v[206:209], v[70:73]
	v_mfma_f32_16x16x32_bf16 v[66:69], v[154:157], v[206:209], v[66:69]
	v_mfma_f32_16x16x32_bf16 v[118:121], v[150:153], v[178:181], v[118:121]
	v_mfma_f32_16x16x32_bf16 v[114:117], v[170:173], v[178:181], v[114:117]
	v_mfma_f32_16x16x32_bf16 v[102:105], v[150:153], v[186:189], v[102:105]
	v_mfma_f32_16x16x32_bf16 v[98:101], v[170:173], v[186:189], v[98:101]
	v_mfma_f32_16x16x32_bf16 v[86:89], v[150:153], v[202:205], v[86:89]
	v_mfma_f32_16x16x32_bf16 v[82:85], v[170:173], v[202:205], v[82:85]
	v_mfma_f32_16x16x32_bf16 v[70:73], v[150:153], v[210:213], v[70:73]
	v_mfma_f32_16x16x32_bf16 v[66:69], v[170:173], v[210:213], v[66:69]
	s_setprio 0
	s_barrier
	s_add_i32 s72, s85, s42
	v_lshl_add_u64 v[214:215], v[214:215], 0, s[34:35]
	s_mov_b32 m0, s72
	ds_read_b128 v[174:177], v200 offset:49152
	ds_read_b128 v[178:181], v200 offset:50176
	ds_read_b128 v[182:185], v200 offset:51200
	ds_read_b128 v[186:189], v200 offset:52224
	ds_read_b128 v[190:193], v200 offset:53248
	ds_read_b128 v[202:205], v200 offset:54272
	ds_read_b128 v[206:209], v200 offset:55296
	ds_read_b128 v[210:213], v200 offset:56320
	global_load_lds_dwordx4 v[214:215], off
	v_lshl_add_u64 v[214:215], v[216:217], 0, s[34:35]
	s_add_i32 m0, s72, 0x2000
	s_add_i32 s72, s87, s42
	global_load_lds_dwordx4 v[214:215], off
	v_lshl_add_u64 v[214:215], v[218:219], 0, s[34:35]
	s_mov_b32 m0, s72
	s_nop 0
	global_load_lds_dwordx4 v[214:215], off
	v_lshl_add_u64 v[214:215], v[228:229], 0, s[34:35]
	s_add_i32 m0, s72, 0x2000
	s_nop 0
	global_load_lds_dwordx4 v[214:215], off
	v_lshl_add_u64 v[214:215], v[230:231], 0, s[34:35]
	s_mov_b32 m0, s79
	s_nop 0
	global_load_lds_dwordx4 v[214:215], off
	v_lshl_add_u64 v[214:215], v[232:233], 0, s[34:35]
	s_mov_b32 m0, s80
	s_nop 0
	global_load_lds_dwordx4 v[214:215], off
	s_waitcnt vmcnt(8)
	s_waitcnt lgkmcnt(0)
	s_barrier
	s_setprio 1
	s_waitcnt lgkmcnt(0)
	v_mfma_f32_16x16x32_bf16 v[62:65], v[130:133], v[174:177], v[62:65]
	v_mfma_f32_16x16x32_bf16 v[58:61], v[138:141], v[174:177], v[58:61]
	v_mfma_f32_16x16x32_bf16 v[46:49], v[130:133], v[182:185], v[46:49]
	v_mfma_f32_16x16x32_bf16 v[42:45], v[138:141], v[182:185], v[42:45]
	v_mfma_f32_16x16x32_bf16 v[30:33], v[130:133], v[190:193], v[30:33]
	v_mfma_f32_16x16x32_bf16 v[26:29], v[138:141], v[190:193], v[26:29]
	v_mfma_f32_16x16x32_bf16 v[14:17], v[130:133], v[206:209], v[14:17]
	v_mfma_f32_16x16x32_bf16 v[10:13], v[138:141], v[206:209], v[10:13]
	v_mfma_f32_16x16x32_bf16 v[62:65], v[134:137], v[178:181], v[62:65]
	v_mfma_f32_16x16x32_bf16 v[58:61], v[142:145], v[178:181], v[58:61]
	v_mfma_f32_16x16x32_bf16 v[46:49], v[134:137], v[186:189], v[46:49]
	v_mfma_f32_16x16x32_bf16 v[42:45], v[142:145], v[186:189], v[42:45]
	v_mfma_f32_16x16x32_bf16 v[30:33], v[134:137], v[202:205], v[30:33]
	v_mfma_f32_16x16x32_bf16 v[26:29], v[142:145], v[202:205], v[26:29]
	v_mfma_f32_16x16x32_bf16 v[14:17], v[134:137], v[210:213], v[14:17]
	v_mfma_f32_16x16x32_bf16 v[10:13], v[142:145], v[210:213], v[10:13]
	s_setprio 0
	s_setprio 1
	v_mfma_f32_16x16x32_bf16 v[54:57], v[146:149], v[174:177], v[54:57]
	v_mfma_f32_16x16x32_bf16 v[50:53], v[154:157], v[174:177], v[50:53]
	v_mfma_f32_16x16x32_bf16 v[38:41], v[146:149], v[182:185], v[38:41]
	v_mfma_f32_16x16x32_bf16 v[34:37], v[154:157], v[182:185], v[34:37]
	v_mfma_f32_16x16x32_bf16 v[22:25], v[146:149], v[190:193], v[22:25]
	v_mfma_f32_16x16x32_bf16 v[18:21], v[154:157], v[190:193], v[18:21]
	v_mfma_f32_16x16x32_bf16 v[6:9], v[146:149], v[206:209], v[6:9]
	v_mfma_f32_16x16x32_bf16 v[2:5], v[154:157], v[206:209], v[2:5]
	v_mfma_f32_16x16x32_bf16 v[54:57], v[150:153], v[178:181], v[54:57]
	v_mfma_f32_16x16x32_bf16 v[50:53], v[170:173], v[178:181], v[50:53]
	v_mfma_f32_16x16x32_bf16 v[38:41], v[150:153], v[186:189], v[38:41]
	v_mfma_f32_16x16x32_bf16 v[34:37], v[170:173], v[186:189], v[34:37]
	v_mfma_f32_16x16x32_bf16 v[22:25], v[150:153], v[202:205], v[22:25]
	v_mfma_f32_16x16x32_bf16 v[18:21], v[170:173], v[202:205], v[18:21]
	v_mfma_f32_16x16x32_bf16 v[6:9], v[150:153], v[210:213], v[6:9]
	v_mfma_f32_16x16x32_bf16 v[2:5], v[170:173], v[210:213], v[2:5]
	s_setprio 0
	s_barrier
	s_add_u32 s40, s40, 0x100
	s_addc_u32 s41, s41, 0
	s_add_u32 s82, s82, 0x100
	s_addc_u32 s83, s83, 0
	s_cmp_ge_u32 s84, s78
	s_mov_b32 s72, s84
	s_cbranch_scc0 .LBB0_363
	v_lshl_add_u32 v172, s27, 8, v197
	v_lshl_add_u32 v174, s50, 8, v1
	v_ashrrev_i32_e32 v173, 31, v172
	v_ashrrev_i32_e32 v175, 31, v174
	v_lshl_add_u64 v[170:171], v[172:173], 1, s[30:31]
	v_lshlrev_b64 v[130:131], 11, v[174:175]
	v_or_b32_e32 v184, 16, v174
	v_lshl_add_u64 v[188:189], v[170:171], 0, v[130:131]
	v_ashrrev_i32_e32 v185, 31, v184
	v_or_b32_e32 v180, 32, v174
	global_load_dwordx4 v[202:205], v[188:189], off
	global_load_dwordx4 v[154:157], v[188:189], off offset:256
	v_lshlrev_b64 v[130:131], 11, v[184:185]
	v_ashrrev_i32_e32 v181, 31, v180
	v_or_b32_e32 v176, 48, v174
	v_lshl_add_u64 v[186:187], v[170:171], 0, v[130:131]
	v_lshlrev_b64 v[130:131], 11, v[180:181]
	v_ashrrev_i32_e32 v177, 31, v176
	v_lshl_add_u64 v[182:183], v[170:171], 0, v[130:131]
	v_lshlrev_b64 v[130:131], 11, v[176:177]
	v_lshl_add_u64 v[178:179], v[170:171], 0, v[130:131]
	global_load_dwordx4 v[150:153], v[186:187], off
	global_load_dwordx4 v[146:149], v[186:187], off offset:256
	global_load_dwordx4 v[142:145], v[182:183], off
	global_load_dwordx4 v[138:141], v[182:183], off offset:256
	global_load_dwordx4 v[134:137], v[178:179], off
	global_load_dwordx4 v[130:133], v[178:179], off offset:256
	v_cndmask_b32_e64 v190, 0, 1, s[54:55]
	v_lshlrev_b64 v[192:193], 10, v[174:175]
	v_cmp_ne_u32_e64 s[40:41], 1, v190
	v_lshl_add_u64 v[190:191], v[192:193], 0, v[172:173]
	s_andn2_b64 vcc, exec, s[54:55]
	v_lshl_add_u64 v[190:191], v[190:191], 2, s[24:25]
	s_waitcnt vmcnt(0)
	v_cvt_f32_f16_e32 v206, v202
	v_cvt_f32_f16_sdwa v207, v202 dst_sel:DWORD dst_unused:UNUSED_PAD src0_sel:WORD_1
	v_cvt_f32_f16_e32 v202, v203
	v_cvt_f32_f16_sdwa v203, v203 dst_sel:DWORD dst_unused:UNUSED_PAD src0_sel:WORD_1
	v_cvt_f32_f16_e32 v208, v204
	v_cvt_f32_f16_e32 v210, v205
	v_cvt_f32_f16_sdwa v211, v205 dst_sel:DWORD dst_unused:UNUSED_PAD src0_sel:WORD_1
	v_cvt_f32_f16_sdwa v209, v204 dst_sel:DWORD dst_unused:UNUSED_PAD src0_sel:WORD_1
	v_pk_add_f32 v[128:129], v[128:129], v[202:203]
	v_pk_add_f32 v[126:127], v[126:127], v[206:207]
	v_pk_add_f32 v[124:125], v[124:125], v[210:211]
	v_pk_add_f32 v[122:123], v[122:123], v[208:209]
	s_cbranch_vccnz .LBB0_428
	global_store_dwordx4 v[190:191], v[126:129], off sc1
	global_store_dwordx4 v[190:191], v[122:125], off offset:16 sc1
	s_cbranch_execnz .LBB0_367
.LBB0_366:
	v_cvt_pk_f16_f32 v202, v126, v127
	v_cvt_pk_f16_f32 v203, v128, v129
	v_cvt_pk_f16_f32 v204, v122, v123
	v_cvt_pk_f16_f32 v205, v124, v125
	v_lshl_add_u64 v[192:193], v[192:193], 1, v[170:171]
	global_store_dwordx4 v[192:193], v[202:205], off sc1
.LBB0_367:
	v_cvt_f32_f16_sdwa v193, v154 dst_sel:DWORD dst_unused:UNUSED_PAD src0_sel:WORD_1
	v_cvt_f32_f16_e32 v192, v154
	v_cvt_f32_f16_sdwa v203, v155 dst_sel:DWORD dst_unused:UNUSED_PAD src0_sel:WORD_1
	v_cvt_f32_f16_e32 v202, v155
	v_cvt_f32_f16_sdwa v155, v156 dst_sel:DWORD dst_unused:UNUSED_PAD src0_sel:WORD_1
	v_cvt_f32_f16_sdwa v205, v157 dst_sel:DWORD dst_unused:UNUSED_PAD src0_sel:WORD_1
	v_cvt_f32_f16_e32 v204, v157
	v_cvt_f32_f16_e32 v154, v156
	v_readlane_b32 s94, v254, 59
	v_pk_add_f32 v[120:121], v[120:121], v[202:203]
	v_pk_add_f32 v[118:119], v[118:119], v[192:193]
	v_pk_add_f32 v[116:117], v[116:117], v[204:205]
	s_and_b64 vcc, exec, s[40:41]
	v_pk_add_f32 v[114:115], v[114:115], v[154:155]
	v_readlane_b32 s95, v254, 60
	v_readlane_b32 s87, v254, 61
	s_cbranch_vccnz .LBB0_429
	global_store_dwordx4 v[190:191], v[118:121], off offset:512 sc1
	global_store_dwordx4 v[190:191], v[114:117], off offset:528 sc1
	s_cbranch_execnz .LBB0_370
.LBB0_369:
	v_cvt_pk_f16_f32 v154, v118, v119
	v_cvt_pk_f16_f32 v155, v120, v121
	v_cvt_pk_f16_f32 v156, v114, v115
	v_cvt_pk_f16_f32 v157, v116, v117
	global_store_dwordx4 v[188:189], v[154:157], off offset:256 sc1

.LBB0_372:
	s_or_b64 exec, exec, s[56:57]
	v_cvt_f32_f16_sdwa v119, v150 dst_sel:DWORD dst_unused:UNUSED_PAD src0_sel:WORD_1
	v_cvt_f32_f16_e32 v118, v150
	v_cvt_f32_f16_sdwa v121, v151 dst_sel:DWORD dst_unused:UNUSED_PAD src0_sel:WORD_1
	v_cvt_f32_f16_e32 v120, v151
	v_cvt_f32_f16_sdwa v123, v152 dst_sel:DWORD dst_unused:UNUSED_PAD src0_sel:WORD_1
	v_cvt_f32_f16_sdwa v125, v153 dst_sel:DWORD dst_unused:UNUSED_PAD src0_sel:WORD_1
	v_cvt_f32_f16_e32 v124, v153
	v_cvt_f32_f16_e32 v122, v152
	v_lshlrev_b64 v[116:117], 10, v[184:185]
	s_waitcnt lgkmcnt(0)
	v_lshl_add_u64 v[114:115], v[116:117], 0, v[172:173]
	v_pk_add_f32 v[112:113], v[112:113], v[120:121]
	v_pk_add_f32 v[110:111], v[110:111], v[118:119]
	v_pk_add_f32 v[108:109], v[108:109], v[124:125]
	v_pk_add_f32 v[106:107], v[106:107], v[122:123]
	s_and_b64 vcc, exec, s[40:41]
	v_lshl_add_u64 v[114:115], v[114:115], 2, s[24:25]
	s_cbranch_vccnz .LBB0_430
	global_store_dwordx4 v[114:115], v[110:113], off sc1
	global_store_dwordx4 v[114:115], v[106:109], off offset:16 sc1
	s_cbranch_execnz .LBB0_375
.LBB0_374:
	v_cvt_pk_f16_f32 v118, v110, v111
	v_cvt_pk_f16_f32 v119, v112, v113
	v_cvt_pk_f16_f32 v120, v106, v107
	v_cvt_pk_f16_f32 v121, v108, v109
	v_lshl_add_u64 v[116:117], v[116:117], 1, v[170:171]
	global_store_dwordx4 v[116:117], v[118:121], off sc1
.LBB0_375:
	v_cvt_f32_f16_sdwa v117, v146 dst_sel:DWORD dst_unused:UNUSED_PAD src0_sel:WORD_1
	v_cvt_f32_f16_e32 v116, v146
	v_cvt_f32_f16_sdwa v119, v147 dst_sel:DWORD dst_unused:UNUSED_PAD src0_sel:WORD_1
	v_cvt_f32_f16_e32 v118, v147
	v_cvt_f32_f16_sdwa v121, v148 dst_sel:DWORD dst_unused:UNUSED_PAD src0_sel:WORD_1
	v_cvt_f32_f16_sdwa v123, v149 dst_sel:DWORD dst_unused:UNUSED_PAD src0_sel:WORD_1
	v_cvt_f32_f16_e32 v122, v149
	v_cvt_f32_f16_e32 v120, v148
	v_pk_add_f32 v[104:105], v[104:105], v[118:119]
	v_pk_add_f32 v[102:103], v[102:103], v[116:117]
	v_pk_add_f32 v[100:101], v[100:101], v[122:123]
	s_and_b64 vcc, exec, s[40:41]
	v_pk_add_f32 v[98:99], v[98:99], v[120:121]
	s_cbranch_vccnz .LBB0_431
	global_store_dwordx4 v[114:115], v[102:105], off offset:512 sc1
	global_store_dwordx4 v[114:115], v[98:101], off offset:528 sc1
	s_cbranch_execnz .LBB0_378
.LBB0_377:
	v_cvt_pk_f16_f32 v114, v102, v103
	v_cvt_pk_f16_f32 v115, v104, v105
	v_cvt_pk_f16_f32 v116, v98, v99
	v_cvt_pk_f16_f32 v117, v100, v101
	global_store_dwordx4 v[186:187], v[114:117], off offset:256 sc1

.LBB0_380:
	s_or_b64 exec, exec, s[56:57]
	v_cvt_f32_f16_sdwa v103, v142 dst_sel:DWORD dst_unused:UNUSED_PAD src0_sel:WORD_1
	v_cvt_f32_f16_e32 v102, v142
	v_cvt_f32_f16_sdwa v105, v143 dst_sel:DWORD dst_unused:UNUSED_PAD src0_sel:WORD_1
	v_cvt_f32_f16_e32 v104, v143
	v_cvt_f32_f16_sdwa v107, v144 dst_sel:DWORD dst_unused:UNUSED_PAD src0_sel:WORD_1
	v_cvt_f32_f16_sdwa v109, v145 dst_sel:DWORD dst_unused:UNUSED_PAD src0_sel:WORD_1
	v_cvt_f32_f16_e32 v108, v145
	v_cvt_f32_f16_e32 v106, v144
	v_lshlrev_b64 v[100:101], 10, v[180:181]
	s_waitcnt lgkmcnt(0)
	v_lshl_add_u64 v[98:99], v[100:101], 0, v[172:173]
	v_pk_add_f32 v[96:97], v[96:97], v[104:105]
	v_pk_add_f32 v[94:95], v[94:95], v[102:103]
	v_pk_add_f32 v[92:93], v[92:93], v[108:109]
	v_pk_add_f32 v[90:91], v[90:91], v[106:107]
	s_and_b64 vcc, exec, s[40:41]
	v_lshl_add_u64 v[98:99], v[98:99], 2, s[24:25]
	s_cbranch_vccnz .LBB0_432
	global_store_dwordx4 v[98:99], v[94:97], off sc1
	global_store_dwordx4 v[98:99], v[90:93], off offset:16 sc1
	s_cbranch_execnz .LBB0_383
.LBB0_382:
	v_cvt_pk_f16_f32 v102, v94, v95
	v_cvt_pk_f16_f32 v103, v96, v97
	v_cvt_pk_f16_f32 v104, v90, v91
	v_cvt_pk_f16_f32 v105, v92, v93
	v_lshl_add_u64 v[100:101], v[100:101], 1, v[170:171]
	global_store_dwordx4 v[100:101], v[102:105], off sc1
.LBB0_383:
	v_cvt_f32_f16_sdwa v101, v138 dst_sel:DWORD dst_unused:UNUSED_PAD src0_sel:WORD_1
	v_cvt_f32_f16_e32 v100, v138
	v_cvt_f32_f16_sdwa v103, v139 dst_sel:DWORD dst_unused:UNUSED_PAD src0_sel:WORD_1
	v_cvt_f32_f16_e32 v102, v139
	v_cvt_f32_f16_sdwa v105, v140 dst_sel:DWORD dst_unused:UNUSED_PAD src0_sel:WORD_1
	v_cvt_f32_f16_sdwa v107, v141 dst_sel:DWORD dst_unused:UNUSED_PAD src0_sel:WORD_1
	v_cvt_f32_f16_e32 v106, v141
	v_cvt_f32_f16_e32 v104, v140
	v_pk_add_f32 v[88:89], v[88:89], v[102:103]
	v_pk_add_f32 v[86:87], v[86:87], v[100:101]
	v_pk_add_f32 v[84:85], v[84:85], v[106:107]
	s_and_b64 vcc, exec, s[40:41]
	v_pk_add_f32 v[82:83], v[82:83], v[104:105]
	s_cbranch_vccnz .LBB0_433
	global_store_dwordx4 v[98:99], v[86:89], off offset:512 sc1
	global_store_dwordx4 v[98:99], v[82:85], off offset:528 sc1
	s_cbranch_execnz .LBB0_386
.LBB0_385:
	v_cvt_pk_f16_f32 v98, v86, v87
	v_cvt_pk_f16_f32 v99, v88, v89
	v_cvt_pk_f16_f32 v100, v82, v83
	v_cvt_pk_f16_f32 v101, v84, v85
	global_store_dwordx4 v[182:183], v[98:101], off offset:256 sc1

.LBB0_388:
	s_or_b64 exec, exec, s[56:57]
	v_cvt_f32_f16_sdwa v87, v134 dst_sel:DWORD dst_unused:UNUSED_PAD src0_sel:WORD_1
	v_cvt_f32_f16_e32 v86, v134
	v_cvt_f32_f16_sdwa v89, v135 dst_sel:DWORD dst_unused:UNUSED_PAD src0_sel:WORD_1
	v_cvt_f32_f16_e32 v88, v135
	v_cvt_f32_f16_sdwa v91, v136 dst_sel:DWORD dst_unused:UNUSED_PAD src0_sel:WORD_1
	v_cvt_f32_f16_sdwa v93, v137 dst_sel:DWORD dst_unused:UNUSED_PAD src0_sel:WORD_1
	v_cvt_f32_f16_e32 v92, v137
	v_cvt_f32_f16_e32 v90, v136
	v_lshlrev_b64 v[84:85], 10, v[176:177]
	s_waitcnt lgkmcnt(0)
	v_lshl_add_u64 v[82:83], v[84:85], 0, v[172:173]
	v_pk_add_f32 v[80:81], v[80:81], v[88:89]
	v_pk_add_f32 v[78:79], v[78:79], v[86:87]
	v_pk_add_f32 v[76:77], v[76:77], v[92:93]
	v_pk_add_f32 v[74:75], v[74:75], v[90:91]
	s_and_b64 vcc, exec, s[40:41]
	v_lshl_add_u64 v[82:83], v[82:83], 2, s[24:25]
	s_cbranch_vccnz .LBB0_434
	global_store_dwordx4 v[82:83], v[78:81], off sc1
	global_store_dwordx4 v[82:83], v[74:77], off offset:16 sc1
	s_cbranch_execnz .LBB0_391
.LBB0_390:
	v_cvt_pk_f16_f32 v86, v78, v79
	v_cvt_pk_f16_f32 v87, v80, v81
	v_cvt_pk_f16_f32 v88, v74, v75
	v_cvt_pk_f16_f32 v89, v76, v77
	v_lshl_add_u64 v[84:85], v[84:85], 1, v[170:171]
	global_store_dwordx4 v[84:85], v[86:89], off sc1
.LBB0_391:
	v_cvt_f32_f16_sdwa v85, v130 dst_sel:DWORD dst_unused:UNUSED_PAD src0_sel:WORD_1
	v_cvt_f32_f16_e32 v84, v130
	v_cvt_f32_f16_sdwa v87, v131 dst_sel:DWORD dst_unused:UNUSED_PAD src0_sel:WORD_1
	v_cvt_f32_f16_e32 v86, v131
	v_cvt_f32_f16_sdwa v89, v132 dst_sel:DWORD dst_unused:UNUSED_PAD src0_sel:WORD_1
	v_cvt_f32_f16_sdwa v91, v133 dst_sel:DWORD dst_unused:UNUSED_PAD src0_sel:WORD_1
	v_cvt_f32_f16_e32 v90, v133
	v_cvt_f32_f16_e32 v88, v132
	v_pk_add_f32 v[72:73], v[72:73], v[86:87]
	v_pk_add_f32 v[70:71], v[70:71], v[84:85]
	v_pk_add_f32 v[68:69], v[68:69], v[90:91]
	s_and_b64 vcc, exec, s[40:41]
	v_pk_add_f32 v[66:67], v[66:67], v[88:89]
	s_cbranch_vccnz .LBB0_435
	global_store_dwordx4 v[82:83], v[70:73], off offset:512 sc1
	global_store_dwordx4 v[82:83], v[66:69], off offset:528 sc1
	s_cbranch_execnz .LBB0_394
.LBB0_393:
	v_cvt_pk_f16_f32 v82, v70, v71
	v_cvt_pk_f16_f32 v83, v72, v73
	v_cvt_pk_f16_f32 v84, v66, v67
	v_cvt_pk_f16_f32 v85, v68, v69
	global_store_dwordx4 v[178:179], v[82:85], off offset:256 sc1

.LBB0_396:
	s_or_b64 exec, exec, s[56:57]
	v_add_u32_e32 v106, 0x80, v174
	v_ashrrev_i32_e32 v107, 31, v106
	s_waitcnt lgkmcnt(0)
	v_lshlrev_b64 v[66:67], 11, v[106:107]
	v_add_u32_e32 v102, 0x90, v174
	v_lshl_add_u64 v[108:109], v[170:171], 0, v[66:67]
	v_ashrrev_i32_e32 v103, 31, v102
	v_add_u32_e32 v98, 0xa0, v174
	global_load_dwordx4 v[114:117], v[108:109], off
	global_load_dwordx4 v[90:93], v[108:109], off offset:256
	v_lshlrev_b64 v[66:67], 11, v[102:103]
	v_ashrrev_i32_e32 v99, 31, v98
	v_add_u32_e32 v94, 0xb0, v174
	v_lshl_add_u64 v[104:105], v[170:171], 0, v[66:67]
	v_lshlrev_b64 v[66:67], 11, v[98:99]
	v_ashrrev_i32_e32 v95, 31, v94
	v_lshl_add_u64 v[100:101], v[170:171], 0, v[66:67]
	v_lshlrev_b64 v[66:67], 11, v[94:95]
	v_lshl_add_u64 v[96:97], v[170:171], 0, v[66:67]
	global_load_dwordx4 v[86:89], v[104:105], off
	global_load_dwordx4 v[82:85], v[104:105], off offset:256
	global_load_dwordx4 v[78:81], v[100:101], off
	global_load_dwordx4 v[74:77], v[100:101], off offset:256
	global_load_dwordx4 v[70:73], v[96:97], off
	global_load_dwordx4 v[66:69], v[96:97], off offset:256
	v_lshlrev_b64 v[112:113], 10, v[106:107]
	v_lshl_add_u64 v[110:111], v[112:113], 0, v[172:173]
	s_and_b64 vcc, exec, s[40:41]
	v_lshl_add_u64 v[110:111], v[110:111], 2, s[24:25]
	s_waitcnt vmcnt(7)
	v_cvt_f32_f16_e32 v118, v114
	v_cvt_f32_f16_sdwa v119, v114 dst_sel:DWORD dst_unused:UNUSED_PAD src0_sel:WORD_1
	v_cvt_f32_f16_e32 v114, v115
	v_cvt_f32_f16_sdwa v115, v115 dst_sel:DWORD dst_unused:UNUSED_PAD src0_sel:WORD_1
	v_cvt_f32_f16_e32 v120, v116
	v_cvt_f32_f16_e32 v122, v117
	v_cvt_f32_f16_sdwa v123, v117 dst_sel:DWORD dst_unused:UNUSED_PAD src0_sel:WORD_1
	v_cvt_f32_f16_sdwa v121, v116 dst_sel:DWORD dst_unused:UNUSED_PAD src0_sel:WORD_1
	v_pk_add_f32 v[64:65], v[64:65], v[114:115]
	v_pk_add_f32 v[62:63], v[62:63], v[118:119]
	v_pk_add_f32 v[60:61], v[60:61], v[122:123]
	v_pk_add_f32 v[58:59], v[58:59], v[120:121]
	s_cbranch_vccnz .LBB0_436
	global_store_dwordx4 v[110:111], v[62:65], off sc1
	global_store_dwordx4 v[110:111], v[58:61], off offset:16 sc1
	s_cbranch_execnz .LBB0_399
.LBB0_398:
	v_cvt_pk_f16_f32 v114, v62, v63
	v_cvt_pk_f16_f32 v115, v64, v65
	v_cvt_pk_f16_f32 v116, v58, v59
	v_cvt_pk_f16_f32 v117, v60, v61
	v_lshl_add_u64 v[112:113], v[112:113], 1, v[170:171]
	global_store_dwordx4 v[112:113], v[114:117], off sc1
.LBB0_399:
	s_waitcnt vmcnt(6)
	v_cvt_f32_f16_sdwa v113, v90 dst_sel:DWORD dst_unused:UNUSED_PAD src0_sel:WORD_1
	v_cvt_f32_f16_e32 v112, v90
	v_cvt_f32_f16_sdwa v115, v91 dst_sel:DWORD dst_unused:UNUSED_PAD src0_sel:WORD_1
	v_cvt_f32_f16_e32 v114, v91
	v_cvt_f32_f16_sdwa v91, v92 dst_sel:DWORD dst_unused:UNUSED_PAD src0_sel:WORD_1
	v_cvt_f32_f16_sdwa v117, v93 dst_sel:DWORD dst_unused:UNUSED_PAD src0_sel:WORD_1
	v_cvt_f32_f16_e32 v116, v93
	v_cvt_f32_f16_e32 v90, v92
	v_pk_add_f32 v[56:57], v[56:57], v[114:115]
	v_pk_add_f32 v[54:55], v[54:55], v[112:113]
	v_pk_add_f32 v[52:53], v[52:53], v[116:117]
	s_and_b64 vcc, exec, s[40:41]
	v_pk_add_f32 v[50:51], v[50:51], v[90:91]
	s_cbranch_vccnz .LBB0_437
	global_store_dwordx4 v[110:111], v[54:57], off offset:512 sc1
	global_store_dwordx4 v[110:111], v[50:53], off offset:528 sc1
	s_cbranch_execnz .LBB0_402
.LBB0_401:
	v_cvt_pk_f16_f32 v90, v54, v55
	v_cvt_pk_f16_f32 v91, v56, v57
	v_cvt_pk_f16_f32 v92, v50, v51
	v_cvt_pk_f16_f32 v93, v52, v53
	global_store_dwordx4 v[108:109], v[90:93], off offset:256 sc1

.LBB0_404:
	s_or_b64 exec, exec, s[56:57]
	s_waitcnt vmcnt(5)
	v_cvt_f32_f16_sdwa v55, v86 dst_sel:DWORD dst_unused:UNUSED_PAD src0_sel:WORD_1
	v_cvt_f32_f16_e32 v54, v86
	v_cvt_f32_f16_sdwa v57, v87 dst_sel:DWORD dst_unused:UNUSED_PAD src0_sel:WORD_1
	v_cvt_f32_f16_e32 v56, v87
	v_cvt_f32_f16_sdwa v59, v88 dst_sel:DWORD dst_unused:UNUSED_PAD src0_sel:WORD_1
	v_cvt_f32_f16_sdwa v61, v89 dst_sel:DWORD dst_unused:UNUSED_PAD src0_sel:WORD_1
	v_cvt_f32_f16_e32 v60, v89
	v_cvt_f32_f16_e32 v58, v88
	v_lshlrev_b64 v[52:53], 10, v[102:103]
	s_waitcnt lgkmcnt(0)
	v_lshl_add_u64 v[50:51], v[52:53], 0, v[172:173]
	v_pk_add_f32 v[48:49], v[48:49], v[56:57]
	v_pk_add_f32 v[46:47], v[46:47], v[54:55]
	v_pk_add_f32 v[44:45], v[44:45], v[60:61]
	v_pk_add_f32 v[42:43], v[42:43], v[58:59]
	s_and_b64 vcc, exec, s[40:41]
	v_lshl_add_u64 v[50:51], v[50:51], 2, s[24:25]
	s_cbranch_vccnz .LBB0_438
	global_store_dwordx4 v[50:51], v[46:49], off sc1
	global_store_dwordx4 v[50:51], v[42:45], off offset:16 sc1
	s_cbranch_execnz .LBB0_407
.LBB0_406:
	v_cvt_pk_f16_f32 v54, v46, v47
	v_cvt_pk_f16_f32 v55, v48, v49
	v_cvt_pk_f16_f32 v56, v42, v43
	v_cvt_pk_f16_f32 v57, v44, v45
	v_lshl_add_u64 v[52:53], v[52:53], 1, v[170:171]
	global_store_dwordx4 v[52:53], v[54:57], off sc1
.LBB0_407:
	s_waitcnt vmcnt(4)
	v_cvt_f32_f16_sdwa v53, v82 dst_sel:DWORD dst_unused:UNUSED_PAD src0_sel:WORD_1
	v_cvt_f32_f16_e32 v52, v82
	v_cvt_f32_f16_sdwa v55, v83 dst_sel:DWORD dst_unused:UNUSED_PAD src0_sel:WORD_1
	v_cvt_f32_f16_e32 v54, v83
	v_cvt_f32_f16_sdwa v57, v84 dst_sel:DWORD dst_unused:UNUSED_PAD src0_sel:WORD_1
	v_cvt_f32_f16_sdwa v59, v85 dst_sel:DWORD dst_unused:UNUSED_PAD src0_sel:WORD_1
	v_cvt_f32_f16_e32 v58, v85
	v_cvt_f32_f16_e32 v56, v84
	v_pk_add_f32 v[40:41], v[40:41], v[54:55]
	v_pk_add_f32 v[38:39], v[38:39], v[52:53]
	v_pk_add_f32 v[36:37], v[36:37], v[58:59]
	s_and_b64 vcc, exec, s[40:41]
	v_pk_add_f32 v[34:35], v[34:35], v[56:57]
	s_cbranch_vccnz .LBB0_439
	global_store_dwordx4 v[50:51], v[38:41], off offset:512 sc1
	global_store_dwordx4 v[50:51], v[34:37], off offset:528 sc1
	s_cbranch_execnz .LBB0_410
.LBB0_409:
	v_cvt_pk_f16_f32 v50, v38, v39
	v_cvt_pk_f16_f32 v51, v40, v41
	v_cvt_pk_f16_f32 v52, v34, v35
	v_cvt_pk_f16_f32 v53, v36, v37
	global_store_dwordx4 v[104:105], v[50:53], off offset:256 sc1

.LBB0_412:
	s_or_b64 exec, exec, s[56:57]
	s_waitcnt vmcnt(3)
	v_cvt_f32_f16_sdwa v39, v78 dst_sel:DWORD dst_unused:UNUSED_PAD src0_sel:WORD_1
	v_cvt_f32_f16_e32 v38, v78
	v_cvt_f32_f16_sdwa v41, v79 dst_sel:DWORD dst_unused:UNUSED_PAD src0_sel:WORD_1
	v_cvt_f32_f16_e32 v40, v79
	v_cvt_f32_f16_sdwa v43, v80 dst_sel:DWORD dst_unused:UNUSED_PAD src0_sel:WORD_1
	v_cvt_f32_f16_sdwa v45, v81 dst_sel:DWORD dst_unused:UNUSED_PAD src0_sel:WORD_1
	v_cvt_f32_f16_e32 v44, v81
	v_cvt_f32_f16_e32 v42, v80
	v_lshlrev_b64 v[36:37], 10, v[98:99]
	s_waitcnt lgkmcnt(0)
	v_lshl_add_u64 v[34:35], v[36:37], 0, v[172:173]
	v_pk_add_f32 v[32:33], v[32:33], v[40:41]
	v_pk_add_f32 v[30:31], v[30:31], v[38:39]
	v_pk_add_f32 v[28:29], v[28:29], v[44:45]
	v_pk_add_f32 v[26:27], v[26:27], v[42:43]
	s_and_b64 vcc, exec, s[40:41]
	v_lshl_add_u64 v[34:35], v[34:35], 2, s[24:25]
	s_cbranch_vccnz .LBB0_440
	global_store_dwordx4 v[34:35], v[30:33], off sc1
	global_store_dwordx4 v[34:35], v[26:29], off offset:16 sc1
	s_cbranch_execnz .LBB0_415
.LBB0_414:
	v_cvt_pk_f16_f32 v38, v30, v31
	v_cvt_pk_f16_f32 v39, v32, v33
	v_cvt_pk_f16_f32 v40, v26, v27
	v_cvt_pk_f16_f32 v41, v28, v29
	v_lshl_add_u64 v[36:37], v[36:37], 1, v[170:171]
	global_store_dwordx4 v[36:37], v[38:41], off sc1
.LBB0_415:
	s_waitcnt vmcnt(2)
	v_cvt_f32_f16_sdwa v37, v74 dst_sel:DWORD dst_unused:UNUSED_PAD src0_sel:WORD_1
	v_cvt_f32_f16_e32 v36, v74
	v_cvt_f32_f16_sdwa v39, v75 dst_sel:DWORD dst_unused:UNUSED_PAD src0_sel:WORD_1
	v_cvt_f32_f16_e32 v38, v75
	v_cvt_f32_f16_sdwa v41, v76 dst_sel:DWORD dst_unused:UNUSED_PAD src0_sel:WORD_1
	v_cvt_f32_f16_sdwa v43, v77 dst_sel:DWORD dst_unused:UNUSED_PAD src0_sel:WORD_1
	v_cvt_f32_f16_e32 v42, v77
	v_cvt_f32_f16_e32 v40, v76
	v_pk_add_f32 v[24:25], v[24:25], v[38:39]
	v_pk_add_f32 v[22:23], v[22:23], v[36:37]
	v_pk_add_f32 v[20:21], v[20:21], v[42:43]
	s_and_b64 vcc, exec, s[40:41]
	v_pk_add_f32 v[18:19], v[18:19], v[40:41]
	s_cbranch_vccnz .LBB0_441
	global_store_dwordx4 v[34:35], v[22:25], off offset:512 sc1
	global_store_dwordx4 v[34:35], v[18:21], off offset:528 sc1
	s_cbranch_execnz .LBB0_418
.LBB0_417:
	v_cvt_pk_f16_f32 v34, v22, v23
	v_cvt_pk_f16_f32 v35, v24, v25
	v_cvt_pk_f16_f32 v36, v18, v19
	v_cvt_pk_f16_f32 v37, v20, v21
	global_store_dwordx4 v[100:101], v[34:37], off offset:256 sc1

.LBB0_420:
	s_or_b64 exec, exec, s[56:57]
	s_waitcnt vmcnt(1)
	v_cvt_f32_f16_sdwa v23, v70 dst_sel:DWORD dst_unused:UNUSED_PAD src0_sel:WORD_1
	v_cvt_f32_f16_e32 v22, v70
	v_cvt_f32_f16_sdwa v25, v71 dst_sel:DWORD dst_unused:UNUSED_PAD src0_sel:WORD_1
	v_cvt_f32_f16_e32 v24, v71
	v_cvt_f32_f16_sdwa v27, v72 dst_sel:DWORD dst_unused:UNUSED_PAD src0_sel:WORD_1
	v_cvt_f32_f16_sdwa v29, v73 dst_sel:DWORD dst_unused:UNUSED_PAD src0_sel:WORD_1
	v_cvt_f32_f16_e32 v28, v73
	v_cvt_f32_f16_e32 v26, v72
	v_lshlrev_b64 v[20:21], 10, v[94:95]
	s_waitcnt lgkmcnt(0)
	v_lshl_add_u64 v[18:19], v[20:21], 0, v[172:173]
	v_pk_add_f32 v[16:17], v[16:17], v[24:25]
	v_pk_add_f32 v[14:15], v[14:15], v[22:23]
	v_pk_add_f32 v[12:13], v[12:13], v[28:29]
	v_pk_add_f32 v[10:11], v[10:11], v[26:27]
	s_and_b64 vcc, exec, s[40:41]
	v_lshl_add_u64 v[18:19], v[18:19], 2, s[24:25]
	s_cbranch_vccnz .LBB0_442
	global_store_dwordx4 v[18:19], v[14:17], off sc1
	global_store_dwordx4 v[18:19], v[10:13], off offset:16 sc1
	s_cbranch_execnz .LBB0_423
.LBB0_422:
	v_cvt_pk_f16_f32 v22, v14, v15
	v_cvt_pk_f16_f32 v23, v16, v17
	v_cvt_pk_f16_f32 v24, v10, v11
	v_cvt_pk_f16_f32 v25, v12, v13
	v_lshl_add_u64 v[20:21], v[20:21], 1, v[170:171]
	global_store_dwordx4 v[20:21], v[22:25], off sc1
.LBB0_423:
	s_waitcnt vmcnt(0)
	v_cvt_f32_f16_sdwa v21, v66 dst_sel:DWORD dst_unused:UNUSED_PAD src0_sel:WORD_1
	v_cvt_f32_f16_e32 v20, v66
	v_cvt_f32_f16_sdwa v23, v67 dst_sel:DWORD dst_unused:UNUSED_PAD src0_sel:WORD_1
	v_cvt_f32_f16_e32 v22, v67
	v_cvt_f32_f16_sdwa v25, v68 dst_sel:DWORD dst_unused:UNUSED_PAD src0_sel:WORD_1
	v_cvt_f32_f16_sdwa v27, v69 dst_sel:DWORD dst_unused:UNUSED_PAD src0_sel:WORD_1
	v_cvt_f32_f16_e32 v26, v69
	v_cvt_f32_f16_e32 v24, v68
	v_pk_add_f32 v[8:9], v[8:9], v[22:23]
	v_pk_add_f32 v[6:7], v[6:7], v[20:21]
	v_pk_add_f32 v[4:5], v[4:5], v[26:27]
	s_and_b64 vcc, exec, s[40:41]
	v_pk_add_f32 v[2:3], v[2:3], v[24:25]
	s_cbranch_vccnz .LBB0_443
	global_store_dwordx4 v[18:19], v[6:9], off offset:512 sc1
	global_store_dwordx4 v[18:19], v[2:5], off offset:528 sc1
	s_cbranch_execnz .LBB0_426
.LBB0_425:
	v_cvt_pk_f16_f32 v18, v6, v7
	v_cvt_pk_f16_f32 v19, v8, v9
	v_cvt_pk_f16_f32 v20, v2, v3
	v_cvt_pk_f16_f32 v21, v4, v5
	global_store_dwordx4 v[96:97], v[18:21], off offset:256 sc1

.LBB0_677:
	s_ashr_i32 s42, s83, 1
	s_lshl_b32 s43, s83, 8
	s_and_b32 s59, s43, 0x100
	s_ashr_i32 s43, s42, 31
	s_lshl_b64 s[72:73], s[42:43], 9
	s_mov_b32 s43, s51
	s_lshl_b64 s[78:79], s[42:43], 23
	s_cmp_eq_u32 s42, 6
	s_cselect_b32 s43, 0, s59
	s_cselect_b32 s59, 8, 9
	s_cmp_lt_i32 s42, 2
	s_cselect_b32 s73, s73, s79
	s_cselect_b32 s72, s72, s78
	s_cselect_b32 s42, 10, s59
	s_lshl_b64 s[72:73], s[72:73], 1
	s_add_u32 s59, s76, s72
	s_addc_u32 s61, s77, s73
	s_lshl_b32 s72, s82, 10
	s_and_b32 s72, s72, 0x400
	v_add_u32_e32 v170, s72, v176
	ds_read_b32 v172, v170
	s_lshl_b32 s43, s43, 1
	s_add_u32 s43, s59, s43
	s_addc_u32 s59, s61, 0
	s_add_u32 s72, s43, s50
	s_waitcnt lgkmcnt(0)
	v_pk_mul_f32 v[136:137], v[136:137], v[172:173] op_sel_hi:[1,0]
	v_pk_mul_f32 v[134:135], v[134:135], v[172:173] op_sel_hi:[1,0]
	v_pk_mul_f32 v[188:189], v[136:137], v[136:137]
	v_pk_mul_f32 v[190:191], v[134:135], v[134:135]
	v_pk_mul_f32 v[132:133], v[132:133], v[172:173] op_sel_hi:[1,0]
	v_pk_mov_b32 v[192:193], v[190:191], v[188:189] op_sel:[1,0]
	v_mov_b32_e32 v191, v189
	v_pk_mul_f32 v[130:131], v[130:131], v[172:173] op_sel_hi:[1,0]
	v_pk_add_f32 v[188:189], v[192:193], v[190:191]
	v_pk_mul_f32 v[190:191], v[132:133], v[132:133]
	v_pk_mul_f32 v[192:193], v[130:131], v[130:131]
	v_pk_mul_f32 v[128:129], v[128:129], v[172:173] op_sel_hi:[1,0]
	v_pk_mov_b32 v[196:197], v[192:193], v[190:191] op_sel:[1,0]
	v_mov_b32_e32 v193, v191
	v_pk_add_f32 v[190:191], v[196:197], v[192:193]
	v_pk_mul_f32 v[192:193], v[126:127], v[172:173] op_sel_hi:[1,0]
	v_pk_add_f32 v[188:189], v[188:189], v[188:189] op_sel_hi:[0,1]
	v_mul_f32_e32 v126, v192, v192
	v_pk_fma_f32 v[126:127], v[192:193], v[192:193], v[126:127] op_sel_hi:[1,1,0]
	v_pk_add_f32 v[190:191], v[190:191], v[190:191] op_sel_hi:[0,1]
	v_mul_f32_e32 v126, v128, v128
	v_pk_fma_f32 v[196:197], v[128:129], v[128:129], v[126:127] op_sel_hi:[1,1,0]
	v_pk_mul_f32 v[198:199], v[124:125], v[172:173] op_sel_hi:[1,0]
	v_pk_mul_f32 v[172:173], v[122:123], v[172:173] op_sel_hi:[1,0]
	v_mul_f32_e32 v188, v198, v198
	v_mul_f32_e32 v126, v172, v172
	v_mul_f32_e32 v196, v173, v173
	v_mul_f32_e32 v190, v199, v199
	v_pk_add_f32 v[122:123], v[126:127], v[196:197]
	v_pk_add_f32 v[124:125], v[188:189], v[190:191]
	s_addc_u32 s73, s59, 0
	v_pk_add_f32 v[122:123], v[122:123], v[124:125]
	s_lshl_b32 s43, s81, 8
	v_add_f32_e32 v122, v122, v123
	ds_bpermute_b32 v123, v178, v122
	v_add_u32_e32 v124, s43, v174
	s_and_b64 vcc, exec, s[38:39]
	s_mov_b64 s[38:39], -1
	s_waitcnt lgkmcnt(0)
	v_add_f32_e32 v122, v122, v123
	ds_bpermute_b32 v123, v179, v122
	s_waitcnt lgkmcnt(0)
	v_add_f32_e32 v122, v122, v123
	v_fmamk_f32 v122, v122, 0x3c800000, v220
	v_rsq_f32_e32 v125, v122
	v_lshl_add_u64 v[122:123], v[146:147], 1, s[72:73]
	v_cndmask_b32_e64 v188, 1.0, v125, s[40:41]
	v_ashrrev_i32_e32 v125, 31, v124
	v_lshlrev_b64 v[124:125], s42, v[124:125]
	v_lshl_add_u64 v[190:191], v[124:125], 1, v[122:123]
	v_pk_mul_f32 v[124:125], v[134:135], v[188:189] op_sel_hi:[1,0]
	v_pk_mul_f32 v[126:127], v[136:137], v[188:189] op_sel_hi:[1,0]
	v_pk_mul_f32 v[124:125], v[156:157], v[124:125]
	v_pk_mul_f32 v[126:127], v[158:159], v[126:127]
	v_pk_mul_f32 v[130:131], v[130:131], v[188:189] op_sel_hi:[1,0]
	v_pk_mul_f32 v[132:133], v[132:133], v[188:189] op_sel_hi:[1,0]
	v_pk_mul_f32 v[130:131], v[154:155], v[130:131]
	v_pk_mul_f32 v[132:133], v[160:161], v[132:133]
	v_cvt_pk_bf16_f32 v124, v124, v125
	v_cvt_pk_bf16_f32 v125, v126, v127
	v_cvt_pk_bf16_f32 v126, v130, v131
	v_pk_mul_f32 v[130:131], v[198:199], v[188:189] op_sel_hi:[1,0]
	v_cvt_pk_bf16_f32 v127, v132, v133
	global_store_dwordx4 v[190:191], v[124:127], off sc1
	v_pk_mul_f32 v[130:131], v[168:169], v[130:131]
	s_nop 0
	v_pk_mul_f32 v[124:125], v[192:193], v[188:189] op_sel_hi:[1,0]
	v_pk_mul_f32 v[126:127], v[128:129], v[188:189] op_sel_hi:[1,0]
	v_pk_mul_f32 v[124:125], v[164:165], v[124:125]
	v_pk_mul_f32 v[126:127], v[166:167], v[126:127]
	v_pk_mul_f32 v[128:129], v[172:173], v[188:189] op_sel_hi:[1,0]
	v_cvt_pk_bf16_f32 v124, v124, v125
	v_cvt_pk_bf16_f32 v125, v126, v127
	s_nop 0
	v_pk_mul_f32 v[128:129], v[162:163], v[128:129]
	s_nop 0
	v_cvt_pk_bf16_f32 v126, v128, v129
	v_cvt_pk_bf16_f32 v127, v130, v131
	global_store_dwordx4 v[190:191], v[124:127], off offset:64 sc1
	ds_read_b32 v124, v170 offset:64
	s_waitcnt lgkmcnt(0)
	v_pk_mul_f32 v[120:121], v[120:121], v[124:125] op_sel_hi:[1,0]
	v_pk_mul_f32 v[118:119], v[118:119], v[124:125] op_sel_hi:[1,0]
	v_pk_mul_f32 v[126:127], v[120:121], v[120:121]
	v_pk_mul_f32 v[128:129], v[118:119], v[118:119]
	v_pk_mul_f32 v[116:117], v[116:117], v[124:125] op_sel_hi:[1,0]
	v_pk_mov_b32 v[130:131], v[128:129], v[126:127] op_sel:[1,0]
	v_mov_b32_e32 v129, v127
	v_pk_add_f32 v[126:127], v[130:131], v[128:129]
	v_pk_mul_f32 v[114:115], v[114:115], v[124:125] op_sel_hi:[1,0]
	v_pk_add_f32 v[126:127], v[126:127], v[126:127] op_sel_hi:[0,1]
	v_pk_mul_f32 v[128:129], v[116:117], v[116:117]
	v_pk_mul_f32 v[130:131], v[114:115], v[114:115]
	v_pk_mul_f32 v[110:111], v[110:111], v[124:125] op_sel_hi:[1,0]
	v_pk_mov_b32 v[132:133], v[130:131], v[128:129] op_sel:[1,0]
	v_mov_b32_e32 v131, v129
	v_pk_mul_f32 v[112:113], v[112:113], v[124:125] op_sel_hi:[1,0]
	v_mul_f32_e32 v126, v110, v110
	v_pk_add_f32 v[128:129], v[132:133], v[130:131]
	v_pk_fma_f32 v[130:131], v[110:111], v[110:111], v[126:127] op_sel_hi:[1,1,0]
	v_mul_f32_e32 v126, v112, v112
	v_pk_add_f32 v[128:129], v[128:129], v[128:129] op_sel_hi:[0,1]
	v_pk_fma_f32 v[132:133], v[112:113], v[112:113], v[126:127] op_sel_hi:[1,1,0]
	v_pk_mul_f32 v[134:135], v[108:109], v[124:125] op_sel_hi:[1,0]
	v_pk_mul_f32 v[124:125], v[106:107], v[124:125] op_sel_hi:[1,0]
	v_mul_f32_e32 v126, v134, v134
	v_mul_f32_e32 v130, v124, v124
	v_mul_f32_e32 v132, v125, v125
	v_mul_f32_e32 v128, v135, v135
	v_pk_add_f32 v[106:107], v[130:131], v[132:133]
	v_pk_add_f32 v[108:109], v[126:127], v[128:129]
	s_nop 0
	v_pk_add_f32 v[106:107], v[106:107], v[108:109]
	s_nop 0
	v_add_f32_e32 v106, v106, v107
	ds_bpermute_b32 v107, v178, v106
	s_waitcnt lgkmcnt(0)
	v_add_f32_e32 v106, v106, v107
	ds_bpermute_b32 v107, v179, v106
	s_waitcnt lgkmcnt(0)
	v_add_f32_e32 v106, v106, v107
	v_fmamk_f32 v106, v106, 0x3c800000, v220
	v_rsq_f32_e32 v107, v106
	v_add_u32_e32 v106, s43, v180
	v_cndmask_b32_e64 v126, 1.0, v107, s[40:41]
	v_ashrrev_i32_e32 v107, 31, v106
	v_lshlrev_b64 v[106:107], s42, v[106:107]
	v_lshl_add_u64 v[128:129], v[106:107], 1, v[122:123]
	v_pk_mul_f32 v[106:107], v[118:119], v[126:127] op_sel_hi:[1,0]
	v_pk_mul_f32 v[108:109], v[120:121], v[126:127] op_sel_hi:[1,0]
	v_pk_mul_f32 v[106:107], v[156:157], v[106:107]
	v_pk_mul_f32 v[108:109], v[158:159], v[108:109]
	v_pk_mul_f32 v[114:115], v[114:115], v[126:127] op_sel_hi:[1,0]
	v_pk_mul_f32 v[116:117], v[116:117], v[126:127] op_sel_hi:[1,0]
	v_pk_mul_f32 v[114:115], v[154:155], v[114:115]
	v_pk_mul_f32 v[116:117], v[160:161], v[116:117]
	v_cvt_pk_bf16_f32 v106, v106, v107
	v_cvt_pk_bf16_f32 v107, v108, v109
	v_cvt_pk_bf16_f32 v108, v114, v115
	s_nop 0
	v_cvt_pk_bf16_f32 v109, v116, v117
	global_store_dwordx4 v[128:129], v[106:109], off sc1
	s_nop 1
	v_pk_mul_f32 v[106:107], v[110:111], v[126:127] op_sel_hi:[1,0]
	v_pk_mul_f32 v[108:109], v[112:113], v[126:127] op_sel_hi:[1,0]
	v_pk_mul_f32 v[106:107], v[164:165], v[106:107]
	v_pk_mul_f32 v[108:109], v[166:167], v[108:109]
	v_pk_mul_f32 v[110:111], v[124:125], v[126:127] op_sel_hi:[1,0]
	v_pk_mul_f32 v[112:113], v[134:135], v[126:127] op_sel_hi:[1,0]
	v_pk_mul_f32 v[110:111], v[162:163], v[110:111]
	v_pk_mul_f32 v[112:113], v[168:169], v[112:113]
	v_cvt_pk_bf16_f32 v106, v106, v107
	v_cvt_pk_bf16_f32 v107, v108, v109
	v_cvt_pk_bf16_f32 v108, v110, v111
	s_nop 0
	v_cvt_pk_bf16_f32 v109, v112, v113
	global_store_dwordx4 v[128:129], v[106:109], off offset:64 sc1
	ds_read_b32 v106, v170 offset:128
	s_waitcnt lgkmcnt(0)
	v_pk_mul_f32 v[104:105], v[104:105], v[106:107] op_sel_hi:[1,0]
	v_pk_mul_f32 v[102:103], v[102:103], v[106:107] op_sel_hi:[1,0]
	v_pk_mul_f32 v[108:109], v[104:105], v[104:105]
	v_pk_mul_f32 v[110:111], v[102:103], v[102:103]
	v_pk_mul_f32 v[100:101], v[100:101], v[106:107] op_sel_hi:[1,0]
	v_pk_mov_b32 v[112:113], v[110:111], v[108:109] op_sel:[1,0]
	v_mov_b32_e32 v111, v109
	v_pk_add_f32 v[108:109], v[112:113], v[110:111]
	v_pk_mul_f32 v[98:99], v[98:99], v[106:107] op_sel_hi:[1,0]
	v_pk_add_f32 v[108:109], v[108:109], v[108:109] op_sel_hi:[0,1]
	v_pk_mul_f32 v[110:111], v[100:101], v[100:101]
	v_pk_mul_f32 v[112:113], v[98:99], v[98:99]
	v_pk_mul_f32 v[94:95], v[94:95], v[106:107] op_sel_hi:[1,0]
	v_pk_mov_b32 v[114:115], v[112:113], v[110:111] op_sel:[1,0]
	v_mov_b32_e32 v113, v111
	v_pk_mul_f32 v[96:97], v[96:97], v[106:107] op_sel_hi:[1,0]
	v_mul_f32_e32 v108, v94, v94
	v_pk_add_f32 v[110:111], v[114:115], v[112:113]
	v_pk_fma_f32 v[112:113], v[94:95], v[94:95], v[108:109] op_sel_hi:[1,1,0]
	v_mul_f32_e32 v108, v96, v96
	v_pk_add_f32 v[110:111], v[110:111], v[110:111] op_sel_hi:[0,1]
	v_pk_fma_f32 v[114:115], v[96:97], v[96:97], v[108:109] op_sel_hi:[1,1,0]
	v_pk_mul_f32 v[116:117], v[92:93], v[106:107] op_sel_hi:[1,0]
	v_pk_mul_f32 v[106:107], v[90:91], v[106:107] op_sel_hi:[1,0]
	v_mul_f32_e32 v108, v116, v116
	v_mul_f32_e32 v112, v106, v106
	v_mul_f32_e32 v114, v107, v107
	v_mul_f32_e32 v110, v117, v117
	v_pk_add_f32 v[90:91], v[112:113], v[114:115]
	v_pk_add_f32 v[92:93], v[108:109], v[110:111]
	s_nop 0
	v_pk_add_f32 v[90:91], v[90:91], v[92:93]
	s_nop 0
	v_add_f32_e32 v90, v90, v91
	ds_bpermute_b32 v91, v178, v90
	s_waitcnt lgkmcnt(0)
	v_add_f32_e32 v90, v90, v91
	ds_bpermute_b32 v91, v179, v90
	s_waitcnt lgkmcnt(0)
	v_add_f32_e32 v90, v90, v91
	v_fmamk_f32 v90, v90, 0x3c800000, v220
	v_rsq_f32_e32 v91, v90
	v_add_u32_e32 v90, s43, v181
	v_cndmask_b32_e64 v108, 1.0, v91, s[40:41]
	v_ashrrev_i32_e32 v91, 31, v90
	v_lshlrev_b64 v[90:91], s42, v[90:91]
	v_lshl_add_u64 v[110:111], v[90:91], 1, v[122:123]
	v_pk_mul_f32 v[90:91], v[102:103], v[108:109] op_sel_hi:[1,0]
	v_pk_mul_f32 v[92:93], v[104:105], v[108:109] op_sel_hi:[1,0]
	v_pk_mul_f32 v[90:91], v[156:157], v[90:91]
	v_pk_mul_f32 v[92:93], v[158:159], v[92:93]
	v_pk_mul_f32 v[98:99], v[98:99], v[108:109] op_sel_hi:[1,0]
	v_pk_mul_f32 v[100:101], v[100:101], v[108:109] op_sel_hi:[1,0]
	v_pk_mul_f32 v[98:99], v[154:155], v[98:99]
	v_pk_mul_f32 v[100:101], v[160:161], v[100:101]
	v_cvt_pk_bf16_f32 v90, v90, v91
	v_cvt_pk_bf16_f32 v91, v92, v93
	v_cvt_pk_bf16_f32 v92, v98, v99
	s_nop 0
	v_cvt_pk_bf16_f32 v93, v100, v101
	global_store_dwordx4 v[110:111], v[90:93], off sc1
	s_nop 1
	v_pk_mul_f32 v[90:91], v[94:95], v[108:109] op_sel_hi:[1,0]
	v_pk_mul_f32 v[92:93], v[96:97], v[108:109] op_sel_hi:[1,0]
	v_pk_mul_f32 v[90:91], v[164:165], v[90:91]
	v_pk_mul_f32 v[92:93], v[166:167], v[92:93]
	v_pk_mul_f32 v[94:95], v[106:107], v[108:109] op_sel_hi:[1,0]
	v_pk_mul_f32 v[96:97], v[116:117], v[108:109] op_sel_hi:[1,0]
	v_pk_mul_f32 v[94:95], v[162:163], v[94:95]
	v_pk_mul_f32 v[96:97], v[168:169], v[96:97]
	v_cvt_pk_bf16_f32 v90, v90, v91
	v_cvt_pk_bf16_f32 v91, v92, v93
	v_cvt_pk_bf16_f32 v92, v94, v95
	s_nop 0
	v_cvt_pk_bf16_f32 v93, v96, v97
	global_store_dwordx4 v[110:111], v[90:93], off offset:64 sc1
	ds_read_b32 v90, v170 offset:192
	s_waitcnt lgkmcnt(0)
	v_pk_mul_f32 v[88:89], v[88:89], v[90:91] op_sel_hi:[1,0]
	v_pk_mul_f32 v[86:87], v[86:87], v[90:91] op_sel_hi:[1,0]
	v_pk_mul_f32 v[92:93], v[88:89], v[88:89]
	v_pk_mul_f32 v[94:95], v[86:87], v[86:87]
	v_pk_mul_f32 v[84:85], v[84:85], v[90:91] op_sel_hi:[1,0]
	v_pk_mov_b32 v[96:97], v[94:95], v[92:93] op_sel:[1,0]
	v_mov_b32_e32 v95, v93
	v_pk_add_f32 v[92:93], v[96:97], v[94:95]
	v_pk_mul_f32 v[82:83], v[82:83], v[90:91] op_sel_hi:[1,0]
	v_pk_add_f32 v[92:93], v[92:93], v[92:93] op_sel_hi:[0,1]
	v_pk_mul_f32 v[94:95], v[84:85], v[84:85]
	v_pk_mul_f32 v[96:97], v[82:83], v[82:83]
	v_pk_mul_f32 v[78:79], v[78:79], v[90:91] op_sel_hi:[1,0]
	v_pk_mov_b32 v[98:99], v[96:97], v[94:95] op_sel:[1,0]
	v_mov_b32_e32 v97, v95
	v_pk_mul_f32 v[80:81], v[80:81], v[90:91] op_sel_hi:[1,0]
	v_mul_f32_e32 v92, v78, v78
	v_pk_add_f32 v[94:95], v[98:99], v[96:97]
	v_pk_fma_f32 v[96:97], v[78:79], v[78:79], v[92:93] op_sel_hi:[1,1,0]
	v_mul_f32_e32 v92, v80, v80
	v_pk_add_f32 v[94:95], v[94:95], v[94:95] op_sel_hi:[0,1]
	v_pk_fma_f32 v[98:99], v[80:81], v[80:81], v[92:93] op_sel_hi:[1,1,0]
	v_pk_mul_f32 v[100:101], v[76:77], v[90:91] op_sel_hi:[1,0]
	v_pk_mul_f32 v[90:91], v[74:75], v[90:91] op_sel_hi:[1,0]
	v_mul_f32_e32 v92, v100, v100
	v_mul_f32_e32 v96, v90, v90
	v_mul_f32_e32 v98, v91, v91
	v_mul_f32_e32 v94, v101, v101
	v_pk_add_f32 v[74:75], v[96:97], v[98:99]
	v_pk_add_f32 v[76:77], v[92:93], v[94:95]
	s_nop 0
	v_pk_add_f32 v[74:75], v[74:75], v[76:77]
	s_nop 0
	v_add_f32_e32 v74, v74, v75
	ds_bpermute_b32 v75, v178, v74
	s_waitcnt lgkmcnt(0)
	v_add_f32_e32 v74, v74, v75
	ds_bpermute_b32 v75, v179, v74
	s_waitcnt lgkmcnt(0)
	v_add_f32_e32 v74, v74, v75
	v_fmamk_f32 v74, v74, 0x3c800000, v220
	v_rsq_f32_e32 v75, v74
	v_add_u32_e32 v74, s43, v182
	v_cndmask_b32_e64 v92, 1.0, v75, s[40:41]
	v_ashrrev_i32_e32 v75, 31, v74
	v_lshlrev_b64 v[74:75], s42, v[74:75]
	v_lshl_add_u64 v[94:95], v[74:75], 1, v[122:123]
	v_pk_mul_f32 v[74:75], v[86:87], v[92:93] op_sel_hi:[1,0]
	v_pk_mul_f32 v[76:77], v[88:89], v[92:93] op_sel_hi:[1,0]
	v_pk_mul_f32 v[74:75], v[156:157], v[74:75]
	v_pk_mul_f32 v[76:77], v[158:159], v[76:77]
	v_pk_mul_f32 v[82:83], v[82:83], v[92:93] op_sel_hi:[1,0]
	v_pk_mul_f32 v[84:85], v[84:85], v[92:93] op_sel_hi:[1,0]
	v_pk_mul_f32 v[82:83], v[154:155], v[82:83]
	v_pk_mul_f32 v[84:85], v[160:161], v[84:85]
	v_cvt_pk_bf16_f32 v74, v74, v75
	v_cvt_pk_bf16_f32 v75, v76, v77
	v_cvt_pk_bf16_f32 v76, v82, v83
	s_nop 0
	v_cvt_pk_bf16_f32 v77, v84, v85
	global_store_dwordx4 v[94:95], v[74:77], off sc1
	s_nop 1
	v_pk_mul_f32 v[74:75], v[78:79], v[92:93] op_sel_hi:[1,0]
	v_pk_mul_f32 v[76:77], v[80:81], v[92:93] op_sel_hi:[1,0]
	v_pk_mul_f32 v[74:75], v[164:165], v[74:75]
	v_pk_mul_f32 v[76:77], v[166:167], v[76:77]
	v_pk_mul_f32 v[78:79], v[90:91], v[92:93] op_sel_hi:[1,0]
	v_pk_mul_f32 v[80:81], v[100:101], v[92:93] op_sel_hi:[1,0]
	v_pk_mul_f32 v[78:79], v[162:163], v[78:79]
	v_pk_mul_f32 v[80:81], v[168:169], v[80:81]
	v_cvt_pk_bf16_f32 v74, v74, v75
	v_cvt_pk_bf16_f32 v75, v76, v77
	v_cvt_pk_bf16_f32 v76, v78, v79
	s_nop 0
	v_cvt_pk_bf16_f32 v77, v80, v81
	global_store_dwordx4 v[94:95], v[74:77], off offset:64 sc1
	ds_read_b32 v74, v170 offset:512
	s_waitcnt lgkmcnt(0)
	v_pk_mul_f32 v[72:73], v[72:73], v[74:75] op_sel_hi:[1,0]
	v_pk_mul_f32 v[70:71], v[70:71], v[74:75] op_sel_hi:[1,0]
	v_pk_mul_f32 v[76:77], v[72:73], v[72:73]
	v_pk_mul_f32 v[78:79], v[70:71], v[70:71]
	v_pk_mul_f32 v[68:69], v[68:69], v[74:75] op_sel_hi:[1,0]
	v_pk_mov_b32 v[80:81], v[78:79], v[76:77] op_sel:[1,0]
	v_mov_b32_e32 v79, v77
	v_pk_add_f32 v[76:77], v[80:81], v[78:79]
	v_pk_mul_f32 v[66:67], v[66:67], v[74:75] op_sel_hi:[1,0]
	v_pk_add_f32 v[76:77], v[76:77], v[76:77] op_sel_hi:[0,1]
	v_pk_mul_f32 v[78:79], v[68:69], v[68:69]
	v_pk_mul_f32 v[80:81], v[66:67], v[66:67]
	v_pk_mul_f32 v[62:63], v[62:63], v[74:75] op_sel_hi:[1,0]
	v_pk_mov_b32 v[82:83], v[80:81], v[78:79] op_sel:[1,0]
	v_mov_b32_e32 v81, v79
	v_pk_mul_f32 v[64:65], v[64:65], v[74:75] op_sel_hi:[1,0]
	v_mul_f32_e32 v76, v62, v62
	v_pk_add_f32 v[78:79], v[82:83], v[80:81]
	v_pk_fma_f32 v[80:81], v[62:63], v[62:63], v[76:77] op_sel_hi:[1,1,0]
	v_mul_f32_e32 v76, v64, v64
	v_pk_add_f32 v[78:79], v[78:79], v[78:79] op_sel_hi:[0,1]
	v_pk_fma_f32 v[82:83], v[64:65], v[64:65], v[76:77] op_sel_hi:[1,1,0]
	v_pk_mul_f32 v[84:85], v[60:61], v[74:75] op_sel_hi:[1,0]
	v_pk_mul_f32 v[74:75], v[58:59], v[74:75] op_sel_hi:[1,0]
	v_mul_f32_e32 v76, v84, v84
	v_mul_f32_e32 v80, v74, v74
	v_mul_f32_e32 v82, v75, v75
	v_mul_f32_e32 v78, v85, v85
	v_pk_add_f32 v[58:59], v[80:81], v[82:83]
	v_pk_add_f32 v[60:61], v[76:77], v[78:79]
	s_nop 0
	v_pk_add_f32 v[58:59], v[58:59], v[60:61]
	s_nop 0
	v_add_f32_e32 v58, v58, v59
	ds_bpermute_b32 v59, v178, v58
	s_waitcnt lgkmcnt(0)
	v_add_f32_e32 v58, v58, v59
	ds_bpermute_b32 v59, v179, v58
	s_waitcnt lgkmcnt(0)
	v_add_f32_e32 v58, v58, v59
	v_fmamk_f32 v58, v58, 0x3c800000, v220
	v_rsq_f32_e32 v59, v58
	v_add_u32_e32 v58, s43, v183
	v_cndmask_b32_e64 v76, 1.0, v59, s[40:41]
	v_ashrrev_i32_e32 v59, 31, v58
	v_lshlrev_b64 v[58:59], s42, v[58:59]
	v_lshl_add_u64 v[78:79], v[58:59], 1, v[122:123]
	v_pk_mul_f32 v[58:59], v[70:71], v[76:77] op_sel_hi:[1,0]
	v_pk_mul_f32 v[60:61], v[72:73], v[76:77] op_sel_hi:[1,0]
	v_pk_mul_f32 v[58:59], v[156:157], v[58:59]
	v_pk_mul_f32 v[60:61], v[158:159], v[60:61]
	v_pk_mul_f32 v[66:67], v[66:67], v[76:77] op_sel_hi:[1,0]
	v_pk_mul_f32 v[68:69], v[68:69], v[76:77] op_sel_hi:[1,0]
	v_pk_mul_f32 v[66:67], v[154:155], v[66:67]
	v_pk_mul_f32 v[68:69], v[160:161], v[68:69]
	v_cvt_pk_bf16_f32 v58, v58, v59
	v_cvt_pk_bf16_f32 v59, v60, v61
	v_cvt_pk_bf16_f32 v60, v66, v67
	s_nop 0
	v_cvt_pk_bf16_f32 v61, v68, v69
	global_store_dwordx4 v[78:79], v[58:61], off sc1
	s_nop 1
	v_pk_mul_f32 v[58:59], v[62:63], v[76:77] op_sel_hi:[1,0]
	v_pk_mul_f32 v[60:61], v[64:65], v[76:77] op_sel_hi:[1,0]
	v_pk_mul_f32 v[58:59], v[164:165], v[58:59]
	v_pk_mul_f32 v[60:61], v[166:167], v[60:61]
	v_pk_mul_f32 v[62:63], v[74:75], v[76:77] op_sel_hi:[1,0]
	v_pk_mul_f32 v[64:65], v[84:85], v[76:77] op_sel_hi:[1,0]
	v_pk_mul_f32 v[62:63], v[162:163], v[62:63]
	v_pk_mul_f32 v[64:65], v[168:169], v[64:65]
	v_cvt_pk_bf16_f32 v58, v58, v59
	v_cvt_pk_bf16_f32 v59, v60, v61
	v_cvt_pk_bf16_f32 v60, v62, v63
	s_nop 0
	v_cvt_pk_bf16_f32 v61, v64, v65
	global_store_dwordx4 v[78:79], v[58:61], off offset:64 sc1
	ds_read_b32 v58, v170 offset:576
	s_waitcnt lgkmcnt(0)
	v_pk_mul_f32 v[56:57], v[56:57], v[58:59] op_sel_hi:[1,0]
	v_pk_mul_f32 v[54:55], v[54:55], v[58:59] op_sel_hi:[1,0]
	v_pk_mul_f32 v[60:61], v[56:57], v[56:57]
	v_pk_mul_f32 v[62:63], v[54:55], v[54:55]
	v_pk_mul_f32 v[52:53], v[52:53], v[58:59] op_sel_hi:[1,0]
	v_pk_mov_b32 v[64:65], v[62:63], v[60:61] op_sel:[1,0]
	v_mov_b32_e32 v63, v61
	v_pk_add_f32 v[60:61], v[64:65], v[62:63]
	v_pk_mul_f32 v[50:51], v[50:51], v[58:59] op_sel_hi:[1,0]
	v_pk_add_f32 v[60:61], v[60:61], v[60:61] op_sel_hi:[0,1]
	v_pk_mul_f32 v[62:63], v[52:53], v[52:53]
	v_pk_mul_f32 v[64:65], v[50:51], v[50:51]
	v_pk_mul_f32 v[46:47], v[46:47], v[58:59] op_sel_hi:[1,0]
	v_pk_mov_b32 v[66:67], v[64:65], v[62:63] op_sel:[1,0]
	v_mov_b32_e32 v65, v63
	v_pk_mul_f32 v[48:49], v[48:49], v[58:59] op_sel_hi:[1,0]
	v_mul_f32_e32 v60, v46, v46
	v_pk_add_f32 v[62:63], v[66:67], v[64:65]
	v_pk_fma_f32 v[64:65], v[46:47], v[46:47], v[60:61] op_sel_hi:[1,1,0]
	v_mul_f32_e32 v60, v48, v48
	v_pk_add_f32 v[62:63], v[62:63], v[62:63] op_sel_hi:[0,1]
	v_pk_fma_f32 v[66:67], v[48:49], v[48:49], v[60:61] op_sel_hi:[1,1,0]
	v_pk_mul_f32 v[68:69], v[44:45], v[58:59] op_sel_hi:[1,0]
	v_pk_mul_f32 v[58:59], v[42:43], v[58:59] op_sel_hi:[1,0]
	v_mul_f32_e32 v60, v68, v68
	v_mul_f32_e32 v64, v58, v58
	v_mul_f32_e32 v66, v59, v59
	v_mul_f32_e32 v62, v69, v69
	v_pk_add_f32 v[42:43], v[64:65], v[66:67]
	v_pk_add_f32 v[44:45], v[60:61], v[62:63]
	s_nop 0
	v_pk_add_f32 v[42:43], v[42:43], v[44:45]
	s_nop 0
	v_add_f32_e32 v42, v42, v43
	ds_bpermute_b32 v43, v178, v42
	s_waitcnt lgkmcnt(0)
	v_add_f32_e32 v42, v42, v43
	ds_bpermute_b32 v43, v179, v42
	s_waitcnt lgkmcnt(0)
	v_add_f32_e32 v42, v42, v43
	v_fmamk_f32 v42, v42, 0x3c800000, v220
	v_rsq_f32_e32 v43, v42
	v_add_u32_e32 v42, s43, v184
	v_cndmask_b32_e64 v60, 1.0, v43, s[40:41]
	v_ashrrev_i32_e32 v43, 31, v42
	v_lshlrev_b64 v[42:43], s42, v[42:43]
	v_lshl_add_u64 v[62:63], v[42:43], 1, v[122:123]
	v_pk_mul_f32 v[42:43], v[54:55], v[60:61] op_sel_hi:[1,0]
	v_pk_mul_f32 v[44:45], v[56:57], v[60:61] op_sel_hi:[1,0]
	v_pk_mul_f32 v[42:43], v[156:157], v[42:43]
	v_pk_mul_f32 v[44:45], v[158:159], v[44:45]
	v_pk_mul_f32 v[50:51], v[50:51], v[60:61] op_sel_hi:[1,0]
	v_pk_mul_f32 v[52:53], v[52:53], v[60:61] op_sel_hi:[1,0]
	v_pk_mul_f32 v[50:51], v[154:155], v[50:51]
	v_pk_mul_f32 v[52:53], v[160:161], v[52:53]
	v_cvt_pk_bf16_f32 v42, v42, v43
	v_cvt_pk_bf16_f32 v43, v44, v45
	v_cvt_pk_bf16_f32 v44, v50, v51
	s_nop 0
	v_cvt_pk_bf16_f32 v45, v52, v53
	global_store_dwordx4 v[62:63], v[42:45], off sc1
	s_nop 1
	v_pk_mul_f32 v[42:43], v[46:47], v[60:61] op_sel_hi:[1,0]
	v_pk_mul_f32 v[44:45], v[48:49], v[60:61] op_sel_hi:[1,0]
	v_pk_mul_f32 v[42:43], v[164:165], v[42:43]
	v_pk_mul_f32 v[44:45], v[166:167], v[44:45]
	v_pk_mul_f32 v[46:47], v[58:59], v[60:61] op_sel_hi:[1,0]
	v_pk_mul_f32 v[48:49], v[68:69], v[60:61] op_sel_hi:[1,0]
	v_pk_mul_f32 v[46:47], v[162:163], v[46:47]
	v_pk_mul_f32 v[48:49], v[168:169], v[48:49]
	v_cvt_pk_bf16_f32 v42, v42, v43
	v_cvt_pk_bf16_f32 v43, v44, v45
	v_cvt_pk_bf16_f32 v44, v46, v47
	s_nop 0
	v_cvt_pk_bf16_f32 v45, v48, v49
	global_store_dwordx4 v[62:63], v[42:45], off offset:64 sc1
	ds_read_b32 v42, v170 offset:640
	s_waitcnt lgkmcnt(0)
	v_pk_mul_f32 v[40:41], v[40:41], v[42:43] op_sel_hi:[1,0]
	v_pk_mul_f32 v[38:39], v[38:39], v[42:43] op_sel_hi:[1,0]
	v_pk_mul_f32 v[44:45], v[40:41], v[40:41]
	v_pk_mul_f32 v[46:47], v[38:39], v[38:39]
	v_pk_mul_f32 v[36:37], v[36:37], v[42:43] op_sel_hi:[1,0]
	v_pk_mov_b32 v[48:49], v[46:47], v[44:45] op_sel:[1,0]
	v_mov_b32_e32 v47, v45
	v_pk_add_f32 v[44:45], v[48:49], v[46:47]
	v_pk_mul_f32 v[34:35], v[34:35], v[42:43] op_sel_hi:[1,0]
	v_pk_add_f32 v[44:45], v[44:45], v[44:45] op_sel_hi:[0,1]
	v_pk_mul_f32 v[46:47], v[36:37], v[36:37]
	v_pk_mul_f32 v[48:49], v[34:35], v[34:35]
	v_pk_mul_f32 v[30:31], v[30:31], v[42:43] op_sel_hi:[1,0]
	v_pk_mov_b32 v[50:51], v[48:49], v[46:47] op_sel:[1,0]
	v_mov_b32_e32 v49, v47
	v_pk_mul_f32 v[32:33], v[32:33], v[42:43] op_sel_hi:[1,0]
	v_mul_f32_e32 v44, v30, v30
	v_pk_add_f32 v[46:47], v[50:51], v[48:49]
	v_pk_fma_f32 v[48:49], v[30:31], v[30:31], v[44:45] op_sel_hi:[1,1,0]
	v_mul_f32_e32 v44, v32, v32
	v_pk_add_f32 v[46:47], v[46:47], v[46:47] op_sel_hi:[0,1]
	v_pk_fma_f32 v[50:51], v[32:33], v[32:33], v[44:45] op_sel_hi:[1,1,0]
	v_pk_mul_f32 v[52:53], v[28:29], v[42:43] op_sel_hi:[1,0]
	v_pk_mul_f32 v[42:43], v[26:27], v[42:43] op_sel_hi:[1,0]
	v_mul_f32_e32 v44, v52, v52
	v_mul_f32_e32 v48, v42, v42
	v_mul_f32_e32 v50, v43, v43
	v_mul_f32_e32 v46, v53, v53
	v_pk_add_f32 v[26:27], v[48:49], v[50:51]
	v_pk_add_f32 v[28:29], v[44:45], v[46:47]
	s_nop 0
	v_pk_add_f32 v[26:27], v[26:27], v[28:29]
	s_nop 0
	v_add_f32_e32 v26, v26, v27
	ds_bpermute_b32 v27, v178, v26
	s_waitcnt lgkmcnt(0)
	v_add_f32_e32 v26, v26, v27
	ds_bpermute_b32 v27, v179, v26
	s_waitcnt lgkmcnt(0)
	v_add_f32_e32 v26, v26, v27
	v_fmamk_f32 v26, v26, 0x3c800000, v220
	v_rsq_f32_e32 v27, v26
	v_add_u32_e32 v26, s43, v185
	v_cndmask_b32_e64 v44, 1.0, v27, s[40:41]
	v_ashrrev_i32_e32 v27, 31, v26
	v_lshlrev_b64 v[26:27], s42, v[26:27]
	v_lshl_add_u64 v[46:47], v[26:27], 1, v[122:123]
	v_pk_mul_f32 v[26:27], v[38:39], v[44:45] op_sel_hi:[1,0]
	v_pk_mul_f32 v[28:29], v[40:41], v[44:45] op_sel_hi:[1,0]
	v_pk_mul_f32 v[26:27], v[156:157], v[26:27]
	v_pk_mul_f32 v[28:29], v[158:159], v[28:29]
	v_pk_mul_f32 v[34:35], v[34:35], v[44:45] op_sel_hi:[1,0]
	v_pk_mul_f32 v[36:37], v[36:37], v[44:45] op_sel_hi:[1,0]
	v_pk_mul_f32 v[34:35], v[154:155], v[34:35]
	v_pk_mul_f32 v[36:37], v[160:161], v[36:37]
	v_cvt_pk_bf16_f32 v26, v26, v27
	v_cvt_pk_bf16_f32 v27, v28, v29
	v_cvt_pk_bf16_f32 v28, v34, v35
	s_nop 0
	v_cvt_pk_bf16_f32 v29, v36, v37
	global_store_dwordx4 v[46:47], v[26:29], off sc1
	s_nop 1
	v_pk_mul_f32 v[26:27], v[30:31], v[44:45] op_sel_hi:[1,0]
	v_pk_mul_f32 v[28:29], v[32:33], v[44:45] op_sel_hi:[1,0]
	v_pk_mul_f32 v[26:27], v[164:165], v[26:27]
	v_pk_mul_f32 v[28:29], v[166:167], v[28:29]
	v_pk_mul_f32 v[30:31], v[42:43], v[44:45] op_sel_hi:[1,0]
	v_pk_mul_f32 v[32:33], v[52:53], v[44:45] op_sel_hi:[1,0]
	v_pk_mul_f32 v[30:31], v[162:163], v[30:31]
	v_pk_mul_f32 v[32:33], v[168:169], v[32:33]
	v_cvt_pk_bf16_f32 v26, v26, v27
	v_cvt_pk_bf16_f32 v27, v28, v29
	v_cvt_pk_bf16_f32 v28, v30, v31
	s_nop 0
	v_cvt_pk_bf16_f32 v29, v32, v33
	global_store_dwordx4 v[46:47], v[26:29], off offset:64 sc1
	ds_read_b32 v26, v170 offset:704
	s_waitcnt lgkmcnt(0)
	v_pk_mul_f32 v[24:25], v[24:25], v[26:27] op_sel_hi:[1,0]
	v_pk_mul_f32 v[22:23], v[22:23], v[26:27] op_sel_hi:[1,0]
	v_pk_mul_f32 v[28:29], v[24:25], v[24:25]
	v_pk_mul_f32 v[30:31], v[22:23], v[22:23]
	v_pk_mul_f32 v[20:21], v[20:21], v[26:27] op_sel_hi:[1,0]
	v_pk_mov_b32 v[32:33], v[30:31], v[28:29] op_sel:[1,0]
	v_mov_b32_e32 v31, v29
	v_pk_add_f32 v[28:29], v[32:33], v[30:31]
	v_pk_mul_f32 v[18:19], v[18:19], v[26:27] op_sel_hi:[1,0]
	v_pk_add_f32 v[28:29], v[28:29], v[28:29] op_sel_hi:[0,1]
	v_pk_mul_f32 v[30:31], v[20:21], v[20:21]
	v_pk_mul_f32 v[32:33], v[18:19], v[18:19]
	v_pk_mul_f32 v[14:15], v[14:15], v[26:27] op_sel_hi:[1,0]
	v_pk_mov_b32 v[34:35], v[32:33], v[30:31] op_sel:[1,0]
	v_mov_b32_e32 v33, v31
	v_pk_mul_f32 v[16:17], v[16:17], v[26:27] op_sel_hi:[1,0]
	v_mul_f32_e32 v28, v14, v14
	v_pk_add_f32 v[30:31], v[34:35], v[32:33]
	v_pk_fma_f32 v[32:33], v[14:15], v[14:15], v[28:29] op_sel_hi:[1,1,0]
	v_mul_f32_e32 v28, v16, v16
	v_pk_add_f32 v[30:31], v[30:31], v[30:31] op_sel_hi:[0,1]
	v_pk_fma_f32 v[34:35], v[16:17], v[16:17], v[28:29] op_sel_hi:[1,1,0]
	v_pk_mul_f32 v[36:37], v[12:13], v[26:27] op_sel_hi:[1,0]
	v_pk_mul_f32 v[26:27], v[10:11], v[26:27] op_sel_hi:[1,0]
	v_mul_f32_e32 v28, v36, v36
	v_mul_f32_e32 v32, v26, v26
	v_mul_f32_e32 v34, v27, v27
	v_mul_f32_e32 v30, v37, v37
	v_pk_add_f32 v[10:11], v[32:33], v[34:35]
	v_pk_add_f32 v[12:13], v[28:29], v[30:31]
	s_nop 0
	v_pk_add_f32 v[10:11], v[10:11], v[12:13]
	s_nop 0
	v_add_f32_e32 v10, v10, v11
	ds_bpermute_b32 v11, v178, v10
	s_waitcnt lgkmcnt(0)
	v_add_f32_e32 v10, v10, v11
	ds_bpermute_b32 v11, v179, v10
	s_waitcnt lgkmcnt(0)
	v_add_f32_e32 v10, v10, v11
	v_fmamk_f32 v10, v10, 0x3c800000, v220
	v_rsq_f32_e32 v11, v10
	v_add_u32_e32 v10, s43, v186
	v_cndmask_b32_e64 v28, 1.0, v11, s[40:41]
	v_ashrrev_i32_e32 v11, 31, v10
	v_lshlrev_b64 v[10:11], s42, v[10:11]
	v_lshl_add_u64 v[30:31], v[10:11], 1, v[122:123]
	v_pk_mul_f32 v[10:11], v[22:23], v[28:29] op_sel_hi:[1,0]
	v_pk_mul_f32 v[12:13], v[24:25], v[28:29] op_sel_hi:[1,0]
	v_pk_mul_f32 v[10:11], v[156:157], v[10:11]
	v_pk_mul_f32 v[12:13], v[158:159], v[12:13]
	v_pk_mul_f32 v[18:19], v[18:19], v[28:29] op_sel_hi:[1,0]
	v_pk_mul_f32 v[20:21], v[20:21], v[28:29] op_sel_hi:[1,0]
	v_pk_mul_f32 v[18:19], v[154:155], v[18:19]
	v_pk_mul_f32 v[20:21], v[160:161], v[20:21]
	v_cvt_pk_bf16_f32 v10, v10, v11
	v_cvt_pk_bf16_f32 v11, v12, v13
	v_cvt_pk_bf16_f32 v12, v18, v19
	s_nop 0
	v_cvt_pk_bf16_f32 v13, v20, v21
	global_store_dwordx4 v[30:31], v[10:13], off sc1
	s_nop 1
	v_pk_mul_f32 v[10:11], v[14:15], v[28:29] op_sel_hi:[1,0]
	v_pk_mul_f32 v[12:13], v[16:17], v[28:29] op_sel_hi:[1,0]
	v_pk_mul_f32 v[10:11], v[164:165], v[10:11]
	v_pk_mul_f32 v[12:13], v[166:167], v[12:13]
	v_pk_mul_f32 v[14:15], v[26:27], v[28:29] op_sel_hi:[1,0]
	v_pk_mul_f32 v[16:17], v[36:37], v[28:29] op_sel_hi:[1,0]
	v_pk_mul_f32 v[14:15], v[162:163], v[14:15]
	v_pk_mul_f32 v[16:17], v[168:169], v[16:17]
	v_cvt_pk_bf16_f32 v10, v10, v11
	v_cvt_pk_bf16_f32 v11, v12, v13
	v_cvt_pk_bf16_f32 v12, v14, v15
	s_nop 0
	v_cvt_pk_bf16_f32 v13, v16, v17
	global_store_dwordx4 v[30:31], v[10:13], off offset:64 sc1
	s_cbranch_vccnz .LBB0_660
	s_waitcnt vmcnt(0)
	v_add_f32_e32 v10, v6, v7
	v_add_f32_e32 v11, v8, v9
	v_add_f32_e32 v10, v10, v11
	v_add_f32_e32 v11, v2, v3
	v_add_f32_e32 v12, v4, v5
	v_add_f32_e32 v11, v11, v12
	v_add_f32_e32 v10, v11, v10
	ds_bpermute_b32 v11, v1, v10
	s_and_saveexec_b64 s[38:39], s[36:37]
	s_cbranch_execz .LBB0_680
	s_waitcnt lgkmcnt(0)
	v_add_f32_e32 v10, v10, v11
	v_fmamk_f32 v10, v10, 0x3a800000, v220
	v_rsq_f32_e32 v10, v10
	s_lshl_b32 s40, s80, 10
	s_and_b32 s40, s40, 0x400
	v_add_u32_e32 v11, s40, v177
	ds_write_b32 v11, v10
